# v41 + counted vmcnt waits in the EpiResid/EpiGate epilogues (P2, P5a, P5b, P6): each batch load waited at its first use instead of one vmcnt(0)
# speedup vs baseline: 1.0111x; 1.0070x over previous
; __device__ __forceinline__ unsigned cvt_pk_bf16(float lo, float hi) { unsigned r; asm volatile("v_cvt_pk_bf16_f32 %0, %1, %2" : "=v"(r) : "v"(lo), "v"(hi)); return r; }
; __device__ __forceinline__ float bf_lo(unsigned w) { return __uint_as_float(w << 16); }
; __device__ __forceinline__ float bf_hi(unsigned w) { return __uint_as_float(w & 0xffff0000u); }
;     __device__ __forceinline__ void operator()(f32x4 (&acc)[2][2][4][2], const Unit& u, int wr, int wc, int fr, int fq) const {
;     ...
;             for (int m = 0; m < 4; ++m) { const int row = row0 + ai * HALF + m * 16; float s = 0.f;
; #pragma unroll
;                 for (int bj = 0; bj < 2; ++bj) { const size_t o2 = (size_t)row * 1024 + col0 + bj * HALF; const u32x4 p = pre[ai][m][bj]; const f32x4 a0 = acc[ai][bj][m][0], a1 = acc[ai][bj][m][1];
;                     f32x4 o0, o1; o0[0] = bf_lo(p.x) + a0[0] * alpha; o0[1] = bf_hi(p.x) + a0[1] * alpha; o0[2] = bf_lo(p.y) + a0[2] * alpha; o0[3] = bf_hi(p.y) + a0[3] * alpha;
;                     o1[0] = bf_lo(p.z) + a1[0] * alpha; o1[1] = bf_hi(p.z) + a1[1] * alpha; o1[2] = bf_lo(p.w) + a1[2] * alpha; o1[3] = bf_hi(p.w) + a1[3] * alpha;
;                     s += ((o0[0] * o0[0] + o0[1] * o0[1]) + (o0[2] * o0[2] + o0[3] * o0[3])) + ((o1[0] * o1[0] + o1[1] * o1[1]) + (o1[2] * o1[2] + o1[3] * o1[3]));
;                     u32x4 w; w.x = cvt_pk_bf16(o0[0], o0[1]); w.y = cvt_pk_bf16(o0[2], o0[3]); w.z = cvt_pk_bf16(o1[0], o1[1]); w.w = cvt_pk_bf16(o1[2], o1[3]);
;                     *(u32x4*)hb_at(u, ai, m, bj, wr, wc, fr, fq) = w;
;                     if (out) { *(f32x4*)(out + o2) = o0; *(f32x4*)(out + o2 + 4) = o1; } }
;                 s += __shfl_xor(s, 16); s += __shfl_xor(s, 32);
;                 if (ssq && fq == 0) atomicAdd(ssq + row, s); }
.Lnoal_1:
	s_waitcnt vmcnt(15)
	v_lshlrev_b32_e32 v209, 16, v220
	v_and_b32_e32 v219, 0xffff0000, v220
	v_lshlrev_b32_e32 v220, 16, v221
	v_fmac_f32_e32 v220, 0.5, v134
	s_waitcnt vmcnt(14)
	v_lshlrev_b32_e32 v134, 16, v225
	v_and_b32_e32 v221, 0xffff0000, v221
	v_lshlrev_b32_e32 v228, 16, v222
	v_and_b32_e32 v222, 0xffff0000, v222
	v_lshlrev_b32_e32 v229, 16, v223
	v_and_b32_e32 v223, 0xffff0000, v223
	v_fmac_f32_e32 v134, 0.5, v122
	v_and_b32_e32 v122, 0xffff0000, v226
	v_fmac_f32_e32 v219, 0.5, v133
	v_fmac_f32_e32 v221, 0.5, v135
	v_fmac_f32_e32 v222, 0.5, v129
	v_fmac_f32_e32 v223, 0.5, v131
	v_and_b32_e32 v133, 0xffff0000, v224
	v_and_b32_e32 v135, 0xffff0000, v225
	v_fmac_f32_e32 v122, 0.5, v117
	v_lshlrev_b32_e32 v117, 16, v227
	v_fmac_f32_e32 v209, 0.5, v132
	v_fmac_f32_e32 v228, 0.5, v128
	v_fmac_f32_e32 v229, 0.5, v130
	v_lshlrev_b32_e32 v132, 16, v224
	v_lshlrev_b32_e32 v224, 16, v226
	v_mul_f32_e32 v225, v219, v219
	v_mul_f32_e32 v230, v221, v221
	v_mul_f32_e32 v231, v222, v222
	v_mul_f32_e32 v232, v223, v223
	v_fmac_f32_e32 v133, 0.5, v121
	v_fmac_f32_e32 v135, 0.5, v123
	v_fmac_f32_e32 v117, 0.5, v118
	v_and_b32_e32 v118, 0xffff0000, v227
	v_fmac_f32_e32 v132, 0.5, v120
	v_fmac_f32_e32 v225, v209, v209
	v_fmac_f32_e32 v230, v220, v220
	v_fmac_f32_e32 v231, v228, v228
	v_fmac_f32_e32 v232, v229, v229
	v_fmac_f32_e32 v224, 0.5, v116
	v_fmac_f32_e32 v118, 0.5, v119
	v_mul_f32_e32 v116, v133, v133
	v_mul_f32_e32 v119, v135, v135
	v_add_f32_e32 v120, v225, v230
	v_add_f32_e32 v121, v231, v232
	v_fmac_f32_e32 v116, v132, v132
	v_fmac_f32_e32 v119, v134, v134
	v_add_f32_e32 v120, v120, v121
	v_add_f32_e32 v116, v116, v119
	v_mul_f32_e32 v119, v122, v122
	v_mul_f32_e32 v121, v118, v118
	v_fmac_f32_e32 v119, v224, v224
	v_fmac_f32_e32 v121, v117, v117
	v_add_f32_e32 v119, v119, v121
	v_cvt_pk_bf16_f32 v128, v209, v219
	v_add_f32_e32 v116, v116, v119
	v_and_b32_e32 v121, 64, v215
	v_cvt_pk_bf16_f32 v129, v220, v221
	v_cvt_pk_bf16_f32 v130, v228, v222
	v_cvt_pk_bf16_f32 v131, v229, v223
	global_store_dwordx4 v[216:217], v[128:131], off sc1
	v_add_f32_e32 v119, v120, v116
	v_xor_b32_e32 v116, 16, v215
	v_add_u32_e32 v128, 64, v121
	v_cmp_lt_i32_e32 vcc, v116, v128
	v_cvt_pk_bf16_f32 v120, v132, v133
	v_cvt_pk_bf16_f32 v121, v134, v135
	v_cvt_pk_bf16_f32 v122, v224, v122
	v_cvt_pk_bf16_f32 v123, v117, v118
	v_xor_b32_e32 v117, 32, v215
	s_nop 0
	v_cndmask_b32_e32 v116, v215, v116, vcc
	v_lshlrev_b32_e32 v116, 2, v116
	ds_bpermute_b32 v129, v116, v119
	v_cmp_lt_i32_e32 vcc, v117, v128
	v_ashrrev_i32_e32 v209, 31, v208
	s_waitcnt lgkmcnt(0)
	v_add_f32_e32 v118, v119, v129
	v_cndmask_b32_e32 v117, v215, v117, vcc
	v_lshlrev_b32_e32 v117, 2, v117
	ds_bpermute_b32 v119, v117, v118
	v_lshl_add_u64 v[128:129], s[74:75], 0, v[190:191]
	global_store_dwordx4 v[128:129], v[120:123], off sc1
	s_and_saveexec_b64 s[76:77], s[2:3]
	s_cbranch_execz .LBB0_231
	v_lshl_add_u64 v[120:121], v[208:209], 2, s[10:11]
	s_waitcnt lgkmcnt(0)
	v_add_f32_e32 v118, v118, v119
	global_atomic_add_f32 v[120:121], v118, off
.LBB0_231:
	s_or_b64 exec, exec, s[76:77]
	s_waitcnt vmcnt(15)
	v_lshlrev_b32_e32 v118, 16, v180
	v_fmac_f32_e32 v118, 0.5, v108
	v_and_b32_e32 v108, 0xffff0000, v180
	v_fmac_f32_e32 v108, 0.5, v109
	v_lshlrev_b32_e32 v109, 16, v181
	v_fmac_f32_e32 v109, 0.5, v110
	v_and_b32_e32 v110, 0xffff0000, v181
	v_fmac_f32_e32 v110, 0.5, v111
	v_lshlrev_b32_e32 v111, 16, v182
	s_waitcnt lgkmcnt(0)
	v_and_b32_e32 v119, 0xffff0000, v182
	v_fmac_f32_e32 v111, 0.5, v104
	v_fmac_f32_e32 v119, 0.5, v105
	v_and_b32_e32 v121, 0xffff0000, v183
	v_mul_f32_e32 v104, v108, v108
	v_mul_f32_e32 v105, v110, v110
	v_lshlrev_b32_e32 v120, 16, v183
	v_fmac_f32_e32 v121, 0.5, v107
	v_fmac_f32_e32 v104, v118, v118
	v_fmac_f32_e32 v105, v109, v109
	v_fmac_f32_e32 v120, 0.5, v106
	v_add_f32_e32 v104, v104, v105
	v_mul_f32_e32 v105, v119, v119
	v_mul_f32_e32 v106, v121, v121
	v_fmac_f32_e32 v105, v111, v111
	v_fmac_f32_e32 v106, v120, v120
	v_add_f32_e32 v105, v105, v106
	v_add_f32_e32 v122, v104, v105
	v_cvt_pk_bf16_f32 v104, v118, v108
	s_waitcnt vmcnt(14)
	v_lshlrev_b32_e32 v108, 16, v176
	v_fmac_f32_e32 v108, 0.5, v100
	v_and_b32_e32 v100, 0xffff0000, v176
	v_fmac_f32_e32 v100, 0.5, v101
	v_lshlrev_b32_e32 v101, 16, v177
	v_fmac_f32_e32 v101, 0.5, v102
	v_and_b32_e32 v102, 0xffff0000, v177
	v_cvt_pk_bf16_f32 v105, v109, v110
	v_fmac_f32_e32 v102, 0.5, v103
	v_lshlrev_b32_e32 v103, 16, v178
	v_and_b32_e32 v109, 0xffff0000, v178
	v_cvt_pk_bf16_f32 v106, v111, v119
	v_fmac_f32_e32 v103, 0.5, v96
	v_fmac_f32_e32 v109, 0.5, v97
	v_and_b32_e32 v111, 0xffff0000, v179
	v_mul_f32_e32 v96, v100, v100
	v_mul_f32_e32 v97, v102, v102
	v_lshlrev_b32_e32 v110, 16, v179
	v_fmac_f32_e32 v111, 0.5, v99
	v_fmac_f32_e32 v96, v108, v108
	v_fmac_f32_e32 v97, v101, v101
	v_fmac_f32_e32 v110, 0.5, v98
	v_add_f32_e32 v96, v96, v97
	v_mul_f32_e32 v97, v109, v109
	v_mul_f32_e32 v98, v111, v111
	v_fmac_f32_e32 v97, v103, v103
	v_fmac_f32_e32 v98, v110, v110
	v_add_f32_e32 v97, v97, v98
	v_add_f32_e32 v96, v96, v97
	v_add_f32_e32 v118, v122, v96
	ds_bpermute_b32 v119, v116, v118
	v_lshl_add_u64 v[96:97], s[72:73], 0, v[192:193]
	v_cvt_pk_bf16_f32 v107, v120, v121
	global_store_dwordx4 v[96:97], v[104:107], off sc1
	v_cvt_pk_bf16_f32 v98, v108, v100
	s_waitcnt lgkmcnt(0)
	v_add_f32_e32 v96, v118, v119
	ds_bpermute_b32 v97, v117, v96
	v_cvt_pk_bf16_f32 v99, v101, v102
	v_cvt_pk_bf16_f32 v100, v103, v109
	v_lshl_add_u64 v[102:103], s[74:75], 0, v[192:193]
	v_cvt_pk_bf16_f32 v101, v110, v111
	global_store_dwordx4 v[102:103], v[98:101], off sc1
	s_and_saveexec_b64 s[76:77], s[2:3]
	s_cbranch_execz .LBB0_233
	v_lshl_add_u64 v[98:99], v[208:209], 2, s[10:11]
	s_waitcnt lgkmcnt(0)
	v_add_f32_e32 v96, v96, v97
	global_atomic_add_f32 v[98:99], v96, off offset:64
; __device__ __forceinline__ unsigned cvt_pk_bf16(float lo, float hi) { unsigned r; asm volatile("v_cvt_pk_bf16_f32 %0, %1, %2" : "=v"(r) : "v"(lo), "v"(hi)); return r; }
; __device__ __forceinline__ float bf_lo(unsigned w) { return __uint_as_float(w << 16); }
; __device__ __forceinline__ float bf_hi(unsigned w) { return __uint_as_float(w & 0xffff0000u); }
;     __device__ __forceinline__ void operator()(f32x4 (&acc)[2][2][4][2], const Unit& u, int wr, int wc, int fr, int fq) const {
;     ...
;             for (int m = 0; m < 4; ++m) { const int row = row0 + ai * HALF + m * 16; float s = 0.f;
; #pragma unroll
;                 for (int bj = 0; bj < 2; ++bj) { const size_t o2 = (size_t)row * 1024 + col0 + bj * HALF; const u32x4 p = pre[ai][m][bj]; const f32x4 a0 = acc[ai][bj][m][0], a1 = acc[ai][bj][m][1];
;                     f32x4 o0, o1; o0[0] = bf_lo(p.x) + a0[0] * alpha; o0[1] = bf_hi(p.x) + a0[1] * alpha; o0[2] = bf_lo(p.y) + a0[2] * alpha; o0[3] = bf_hi(p.y) + a0[3] * alpha;
;                     o1[0] = bf_lo(p.z) + a1[0] * alpha; o1[1] = bf_hi(p.z) + a1[1] * alpha; o1[2] = bf_lo(p.w) + a1[2] * alpha; o1[3] = bf_hi(p.w) + a1[3] * alpha;
;                     s += ((o0[0] * o0[0] + o0[1] * o0[1]) + (o0[2] * o0[2] + o0[3] * o0[3])) + ((o1[0] * o1[0] + o1[1] * o1[1]) + (o1[2] * o1[2] + o1[3] * o1[3]));
;                     u32x4 w; w.x = cvt_pk_bf16(o0[0], o0[1]); w.y = cvt_pk_bf16(o0[2], o0[3]); w.z = cvt_pk_bf16(o1[0], o1[1]); w.w = cvt_pk_bf16(o1[2], o1[3]);
;                     *(u32x4*)hb_at(u, ai, m, bj, wr, wc, fr, fq) = w;
;                     if (out) { *(f32x4*)(out + o2) = o0; *(f32x4*)(out + o2 + 4) = o1; } }
;                 s += __shfl_xor(s, 16); s += __shfl_xor(s, 32);
;                 if (ssq && fq == 0) atomicAdd(ssq + row, s); }
.LBB0_233:
	s_or_b64 exec, exec, s[76:77]
	s_waitcnt vmcnt(15)
	v_lshlrev_b32_e32 v96, 16, v172
	v_fmac_f32_e32 v96, 0.5, v92
	v_and_b32_e32 v92, 0xffff0000, v172
	v_fmac_f32_e32 v92, 0.5, v93
	v_lshlrev_b32_e32 v93, 16, v173
	v_fmac_f32_e32 v93, 0.5, v94
	v_and_b32_e32 v94, 0xffff0000, v173
	v_fmac_f32_e32 v94, 0.5, v95
	v_lshlrev_b32_e32 v95, 16, v174
	s_waitcnt lgkmcnt(0)
	v_and_b32_e32 v97, 0xffff0000, v174
	v_fmac_f32_e32 v95, 0.5, v88
	v_fmac_f32_e32 v97, 0.5, v89
	v_and_b32_e32 v99, 0xffff0000, v175
	v_mul_f32_e32 v88, v92, v92
	v_mul_f32_e32 v89, v94, v94
	v_lshlrev_b32_e32 v98, 16, v175
	v_fmac_f32_e32 v99, 0.5, v91
	v_fmac_f32_e32 v88, v96, v96
	v_fmac_f32_e32 v89, v93, v93
	v_fmac_f32_e32 v98, 0.5, v90
	v_add_f32_e32 v88, v88, v89
	v_mul_f32_e32 v89, v97, v97
	v_mul_f32_e32 v90, v99, v99
	v_fmac_f32_e32 v89, v95, v95
	v_fmac_f32_e32 v90, v98, v98
	v_add_f32_e32 v89, v89, v90
	v_add_f32_e32 v100, v88, v89
	v_cvt_pk_bf16_f32 v88, v96, v92
	s_waitcnt vmcnt(14)
	v_lshlrev_b32_e32 v92, 16, v168
	v_fmac_f32_e32 v92, 0.5, v84
	v_and_b32_e32 v84, 0xffff0000, v168
	v_fmac_f32_e32 v84, 0.5, v85
	v_lshlrev_b32_e32 v85, 16, v169
	v_fmac_f32_e32 v85, 0.5, v86
	v_and_b32_e32 v86, 0xffff0000, v169
	v_cvt_pk_bf16_f32 v89, v93, v94
	v_fmac_f32_e32 v86, 0.5, v87
	v_lshlrev_b32_e32 v87, 16, v170
	v_and_b32_e32 v93, 0xffff0000, v170
	v_cvt_pk_bf16_f32 v90, v95, v97
	v_fmac_f32_e32 v87, 0.5, v80
	v_fmac_f32_e32 v93, 0.5, v81
	v_and_b32_e32 v95, 0xffff0000, v171
	v_mul_f32_e32 v80, v84, v84
	v_mul_f32_e32 v81, v86, v86
	v_lshlrev_b32_e32 v94, 16, v171
	v_fmac_f32_e32 v95, 0.5, v83
	v_fmac_f32_e32 v80, v92, v92
	v_fmac_f32_e32 v81, v85, v85
	v_fmac_f32_e32 v94, 0.5, v82
	v_add_f32_e32 v80, v80, v81
	v_mul_f32_e32 v81, v93, v93
	v_mul_f32_e32 v82, v95, v95
	v_fmac_f32_e32 v81, v87, v87
	v_fmac_f32_e32 v82, v94, v94
	v_add_f32_e32 v81, v81, v82
	v_add_f32_e32 v80, v80, v81
	v_add_f32_e32 v96, v100, v80
	ds_bpermute_b32 v97, v116, v96
	v_lshl_add_u64 v[80:81], s[72:73], 0, v[194:195]
	v_cvt_pk_bf16_f32 v91, v98, v99
	global_store_dwordx4 v[80:81], v[88:91], off sc1
	v_cvt_pk_bf16_f32 v82, v92, v84
	s_waitcnt lgkmcnt(0)
	v_add_f32_e32 v80, v96, v97
	ds_bpermute_b32 v81, v117, v80
	v_cvt_pk_bf16_f32 v83, v85, v86
	v_cvt_pk_bf16_f32 v84, v87, v93
	v_lshl_add_u64 v[86:87], s[74:75], 0, v[194:195]
	v_cvt_pk_bf16_f32 v85, v94, v95
	global_store_dwordx4 v[86:87], v[82:85], off sc1
	s_and_saveexec_b64 s[76:77], s[2:3]
	s_cbranch_execz .LBB0_235
	v_lshl_add_u64 v[82:83], v[208:209], 2, s[10:11]
	s_waitcnt lgkmcnt(0)
	v_add_f32_e32 v80, v80, v81
	global_atomic_add_f32 v[82:83], v80, off offset:128
.LBB0_235:
	s_or_b64 exec, exec, s[76:77]
	s_waitcnt vmcnt(15)
	v_lshlrev_b32_e32 v80, 16, v164
	v_fmac_f32_e32 v80, 0.5, v76
	v_and_b32_e32 v76, 0xffff0000, v164
	v_fmac_f32_e32 v76, 0.5, v77
	v_lshlrev_b32_e32 v77, 16, v165
	v_fmac_f32_e32 v77, 0.5, v78
	v_and_b32_e32 v78, 0xffff0000, v165
	v_fmac_f32_e32 v78, 0.5, v79
	v_lshlrev_b32_e32 v79, 16, v166
	s_waitcnt lgkmcnt(0)
	v_and_b32_e32 v81, 0xffff0000, v166
	v_fmac_f32_e32 v79, 0.5, v72
	v_fmac_f32_e32 v81, 0.5, v73
	v_and_b32_e32 v83, 0xffff0000, v167
	v_mul_f32_e32 v72, v76, v76
	v_mul_f32_e32 v73, v78, v78
	v_lshlrev_b32_e32 v82, 16, v167
	v_fmac_f32_e32 v83, 0.5, v75
	v_fmac_f32_e32 v72, v80, v80
	v_fmac_f32_e32 v73, v77, v77
	v_fmac_f32_e32 v82, 0.5, v74
	v_add_f32_e32 v72, v72, v73
	v_mul_f32_e32 v73, v81, v81
	v_mul_f32_e32 v74, v83, v83
	v_fmac_f32_e32 v73, v79, v79
	v_fmac_f32_e32 v74, v82, v82
	v_add_f32_e32 v73, v73, v74
	v_add_f32_e32 v84, v72, v73
	v_cvt_pk_bf16_f32 v72, v80, v76
	s_waitcnt vmcnt(14)
	v_lshlrev_b32_e32 v76, 16, v160
	v_fmac_f32_e32 v76, 0.5, v68
	v_and_b32_e32 v68, 0xffff0000, v160
	v_fmac_f32_e32 v68, 0.5, v69
	v_lshlrev_b32_e32 v69, 16, v161
	v_fmac_f32_e32 v69, 0.5, v70
	v_and_b32_e32 v70, 0xffff0000, v161
	v_cvt_pk_bf16_f32 v73, v77, v78
	v_fmac_f32_e32 v70, 0.5, v71
	v_lshlrev_b32_e32 v71, 16, v162
	v_and_b32_e32 v77, 0xffff0000, v162
	v_cvt_pk_bf16_f32 v74, v79, v81
	v_fmac_f32_e32 v71, 0.5, v64
	v_fmac_f32_e32 v77, 0.5, v65
	v_and_b32_e32 v79, 0xffff0000, v163
	v_mul_f32_e32 v64, v68, v68
	v_mul_f32_e32 v65, v70, v70
	v_lshlrev_b32_e32 v78, 16, v163
	v_fmac_f32_e32 v79, 0.5, v67
	v_fmac_f32_e32 v64, v76, v76
	v_fmac_f32_e32 v65, v69, v69
	v_fmac_f32_e32 v78, 0.5, v66
	v_add_f32_e32 v64, v64, v65
	v_mul_f32_e32 v65, v77, v77
	v_mul_f32_e32 v66, v79, v79
	v_fmac_f32_e32 v65, v71, v71
	v_fmac_f32_e32 v66, v78, v78
	v_add_f32_e32 v65, v65, v66
	v_add_f32_e32 v64, v64, v65
	v_add_f32_e32 v80, v84, v64
	ds_bpermute_b32 v81, v116, v80
	v_lshl_add_u64 v[64:65], s[72:73], 0, v[186:187]
	v_cvt_pk_bf16_f32 v75, v82, v83
	global_store_dwordx4 v[64:65], v[72:75], off sc1
	v_cvt_pk_bf16_f32 v66, v76, v68
	s_waitcnt lgkmcnt(0)
	v_add_f32_e32 v64, v80, v81
	ds_bpermute_b32 v65, v117, v64
	v_cvt_pk_bf16_f32 v67, v69, v70
	v_cvt_pk_bf16_f32 v68, v71, v77
	v_lshl_add_u64 v[70:71], s[74:75], 0, v[186:187]
	v_cvt_pk_bf16_f32 v69, v78, v79
	global_store_dwordx4 v[70:71], v[66:69], off sc1
	s_and_saveexec_b64 s[72:73], s[2:3]
	s_cbranch_execz .LBB0_237
	v_lshl_add_u64 v[66:67], v[208:209], 2, s[10:11]
	s_waitcnt lgkmcnt(0)
	v_add_f32_e32 v64, v64, v65
	global_atomic_add_f32 v[66:67], v64, off offset:192
; __device__ __forceinline__ unsigned cvt_pk_bf16(float lo, float hi) { unsigned r; asm volatile("v_cvt_pk_bf16_f32 %0, %1, %2" : "=v"(r) : "v"(lo), "v"(hi)); return r; }
; __device__ __forceinline__ float bf_lo(unsigned w) { return __uint_as_float(w << 16); }
; __device__ __forceinline__ float bf_hi(unsigned w) { return __uint_as_float(w & 0xffff0000u); }
;     __device__ __forceinline__ void operator()(f32x4 (&acc)[2][2][4][2], const Unit& u, int wr, int wc, int fr, int fq) const {
;     ...
;             for (int m = 0; m < 4; ++m) { const int row = row0 + ai * HALF + m * 16; float s = 0.f;
; #pragma unroll
;                 for (int bj = 0; bj < 2; ++bj) { const size_t o2 = (size_t)row * 1024 + col0 + bj * HALF; const u32x4 p = pre[ai][m][bj]; const f32x4 a0 = acc[ai][bj][m][0], a1 = acc[ai][bj][m][1];
;                     f32x4 o0, o1; o0[0] = bf_lo(p.x) + a0[0] * alpha; o0[1] = bf_hi(p.x) + a0[1] * alpha; o0[2] = bf_lo(p.y) + a0[2] * alpha; o0[3] = bf_hi(p.y) + a0[3] * alpha;
;                     o1[0] = bf_lo(p.z) + a1[0] * alpha; o1[1] = bf_hi(p.z) + a1[1] * alpha; o1[2] = bf_lo(p.w) + a1[2] * alpha; o1[3] = bf_hi(p.w) + a1[3] * alpha;
;                     s += ((o0[0] * o0[0] + o0[1] * o0[1]) + (o0[2] * o0[2] + o0[3] * o0[3])) + ((o1[0] * o1[0] + o1[1] * o1[1]) + (o1[2] * o1[2] + o1[3] * o1[3]));
;                     u32x4 w; w.x = cvt_pk_bf16(o0[0], o0[1]); w.y = cvt_pk_bf16(o0[2], o0[3]); w.z = cvt_pk_bf16(o1[0], o1[1]); w.w = cvt_pk_bf16(o1[2], o1[3]);
;                     *(u32x4*)hb_at(u, ai, m, bj, wr, wc, fr, fq) = w;
;                     if (out) { *(f32x4*)(out + o2) = o0; *(f32x4*)(out + o2 + 4) = o1; } }
;                 s += __shfl_xor(s, 16); s += __shfl_xor(s, 32);
;                 if (ssq && fq == 0) atomicAdd(ssq + row, s); }
.LBB0_237:
	s_or_b64 exec, exec, s[72:73]
	s_waitcnt vmcnt(15)
	v_lshlrev_b32_e32 v64, 16, v156
	v_fmac_f32_e32 v64, 0.5, v60
	v_and_b32_e32 v60, 0xffff0000, v156
	v_fmac_f32_e32 v60, 0.5, v61
	v_lshlrev_b32_e32 v61, 16, v157
	v_fmac_f32_e32 v61, 0.5, v62
	v_and_b32_e32 v62, 0xffff0000, v157
	v_fmac_f32_e32 v62, 0.5, v63
	v_lshlrev_b32_e32 v63, 16, v158
	s_waitcnt lgkmcnt(0)
	v_and_b32_e32 v65, 0xffff0000, v158
	v_fmac_f32_e32 v63, 0.5, v56
	v_fmac_f32_e32 v65, 0.5, v57
	v_and_b32_e32 v67, 0xffff0000, v159
	v_mul_f32_e32 v56, v60, v60
	v_mul_f32_e32 v57, v62, v62
	v_lshlrev_b32_e32 v66, 16, v159
	v_fmac_f32_e32 v67, 0.5, v59
	v_fmac_f32_e32 v56, v64, v64
	v_fmac_f32_e32 v57, v61, v61
	v_fmac_f32_e32 v66, 0.5, v58
	v_add_f32_e32 v56, v56, v57
	v_mul_f32_e32 v57, v65, v65
	v_mul_f32_e32 v58, v67, v67
	v_fmac_f32_e32 v57, v63, v63
	v_fmac_f32_e32 v58, v66, v66
	s_add_u32 s70, s12, s70
	v_add_f32_e32 v57, v57, v58
	s_addc_u32 s71, s13, s71
	v_add_f32_e32 v68, v56, v57
	v_cvt_pk_bf16_f32 v56, v64, v60
	v_cvt_pk_bf16_f32 v57, v61, v62
	v_lshl_add_u64 v[60:61], s[70:71], 0, v[190:191]
	v_cvt_pk_bf16_f32 v58, v63, v65
	v_cvt_pk_bf16_f32 v59, v66, v67
	global_store_dwordx4 v[60:61], v[56:59], off sc1
	s_add_u32 s68, s12, s68
	s_addc_u32 s69, s13, s69
	s_waitcnt vmcnt(15)
	v_lshlrev_b32_e32 v56, 16, v152
	v_fmac_f32_e32 v56, 0.5, v52
	v_and_b32_e32 v52, 0xffff0000, v152
	v_fmac_f32_e32 v52, 0.5, v53
	v_lshlrev_b32_e32 v53, 16, v153
	v_fmac_f32_e32 v53, 0.5, v54
	v_and_b32_e32 v54, 0xffff0000, v153
	v_fmac_f32_e32 v54, 0.5, v55
	v_lshlrev_b32_e32 v55, 16, v154
	v_fmac_f32_e32 v55, 0.5, v48
	v_and_b32_e32 v48, 0xffff0000, v154
	v_fmac_f32_e32 v48, 0.5, v49
	v_lshlrev_b32_e32 v49, 16, v155
	v_and_b32_e32 v57, 0xffff0000, v155
	v_fmac_f32_e32 v49, 0.5, v50
	v_fmac_f32_e32 v57, 0.5, v51
	v_mul_f32_e32 v50, v52, v52
	v_mul_f32_e32 v51, v54, v54
	v_fmac_f32_e32 v50, v56, v56
	v_fmac_f32_e32 v51, v53, v53
	v_add_f32_e32 v50, v50, v51
	v_mul_f32_e32 v51, v48, v48
	v_mul_f32_e32 v58, v57, v57
	v_fmac_f32_e32 v51, v55, v55
	v_fmac_f32_e32 v58, v49, v49
	v_add_f32_e32 v51, v51, v58
	v_add_f32_e32 v50, v50, v51
	v_add_f32_e32 v58, v68, v50
	ds_bpermute_b32 v59, v116, v58
	v_cvt_pk_bf16_f32 v50, v56, v52
	v_cvt_pk_bf16_f32 v51, v53, v54
	v_cvt_pk_bf16_f32 v52, v55, v48
	v_cvt_pk_bf16_f32 v53, v49, v57
	s_waitcnt lgkmcnt(0)
	v_add_f32_e32 v48, v58, v59
	ds_bpermute_b32 v49, v117, v48
	v_lshl_add_u64 v[54:55], s[68:69], 0, v[190:191]
	global_store_dwordx4 v[54:55], v[50:53], off sc1
	s_and_saveexec_b64 s[72:73], s[2:3]
	s_cbranch_execz .LBB0_239
	v_lshl_add_u64 v[50:51], v[208:209], 2, s[10:11]
	s_waitcnt lgkmcnt(0)
	v_add_f32_e32 v48, v48, v49
	global_atomic_add_f32 v[50:51], v48, off offset:512
.LBB0_239:
	s_or_b64 exec, exec, s[72:73]
	s_waitcnt vmcnt(15)
	v_lshlrev_b32_e32 v48, 16, v148
	v_fmac_f32_e32 v48, 0.5, v44
	v_and_b32_e32 v44, 0xffff0000, v148
	v_fmac_f32_e32 v44, 0.5, v45
	v_lshlrev_b32_e32 v45, 16, v149
	v_fmac_f32_e32 v45, 0.5, v46
	v_and_b32_e32 v46, 0xffff0000, v149
	v_fmac_f32_e32 v46, 0.5, v47
	v_lshlrev_b32_e32 v47, 16, v150
	s_waitcnt lgkmcnt(0)
	v_and_b32_e32 v49, 0xffff0000, v150
	v_fmac_f32_e32 v47, 0.5, v40
	v_fmac_f32_e32 v49, 0.5, v41
	v_and_b32_e32 v51, 0xffff0000, v151
	v_mul_f32_e32 v40, v44, v44
	v_mul_f32_e32 v41, v46, v46
	v_lshlrev_b32_e32 v50, 16, v151
	v_fmac_f32_e32 v51, 0.5, v43
	v_fmac_f32_e32 v40, v48, v48
	v_fmac_f32_e32 v41, v45, v45
	v_fmac_f32_e32 v50, 0.5, v42
	v_add_f32_e32 v40, v40, v41
	v_mul_f32_e32 v41, v49, v49
	v_mul_f32_e32 v42, v51, v51
	v_fmac_f32_e32 v41, v47, v47
	v_fmac_f32_e32 v42, v50, v50
	v_add_f32_e32 v41, v41, v42
	v_add_f32_e32 v52, v40, v41
	v_cvt_pk_bf16_f32 v40, v48, v44
	s_waitcnt vmcnt(14)
	v_lshlrev_b32_e32 v44, 16, v144
	v_fmac_f32_e32 v44, 0.5, v36
	v_and_b32_e32 v36, 0xffff0000, v144
	v_fmac_f32_e32 v36, 0.5, v37
	v_lshlrev_b32_e32 v37, 16, v145
	v_fmac_f32_e32 v37, 0.5, v38
	v_and_b32_e32 v38, 0xffff0000, v145
	v_cvt_pk_bf16_f32 v41, v45, v46
	v_fmac_f32_e32 v38, 0.5, v39
	v_lshlrev_b32_e32 v39, 16, v146
	v_and_b32_e32 v45, 0xffff0000, v146
	v_cvt_pk_bf16_f32 v42, v47, v49
	v_fmac_f32_e32 v39, 0.5, v32
	v_fmac_f32_e32 v45, 0.5, v33
	v_and_b32_e32 v47, 0xffff0000, v147
	v_mul_f32_e32 v32, v36, v36
	v_mul_f32_e32 v33, v38, v38
	v_lshlrev_b32_e32 v46, 16, v147
	v_fmac_f32_e32 v47, 0.5, v35
	v_fmac_f32_e32 v32, v44, v44
	v_fmac_f32_e32 v33, v37, v37
	v_fmac_f32_e32 v46, 0.5, v34
	v_add_f32_e32 v32, v32, v33
	v_mul_f32_e32 v33, v45, v45
	v_mul_f32_e32 v34, v47, v47
	v_fmac_f32_e32 v33, v39, v39
	v_fmac_f32_e32 v34, v46, v46
	v_add_f32_e32 v33, v33, v34
	v_add_f32_e32 v32, v32, v33
	v_add_f32_e32 v48, v52, v32
	ds_bpermute_b32 v49, v116, v48
	v_lshl_add_u64 v[32:33], s[70:71], 0, v[192:193]
	v_cvt_pk_bf16_f32 v43, v50, v51
	global_store_dwordx4 v[32:33], v[40:43], off sc1
	v_cvt_pk_bf16_f32 v34, v44, v36
	s_waitcnt lgkmcnt(0)
	v_add_f32_e32 v32, v48, v49
	ds_bpermute_b32 v33, v117, v32
	v_cvt_pk_bf16_f32 v35, v37, v38
	v_cvt_pk_bf16_f32 v36, v39, v45
	v_lshl_add_u64 v[38:39], s[68:69], 0, v[192:193]
	v_cvt_pk_bf16_f32 v37, v46, v47
	global_store_dwordx4 v[38:39], v[34:37], off sc1
	s_and_saveexec_b64 s[72:73], s[2:3]
	s_cbranch_execz .LBB0_241
	v_lshl_add_u64 v[34:35], v[208:209], 2, s[10:11]
	s_waitcnt lgkmcnt(0)
	v_add_f32_e32 v32, v32, v33
	global_atomic_add_f32 v[34:35], v32, off offset:576
; __device__ __forceinline__ unsigned cvt_pk_bf16(float lo, float hi) { unsigned r; asm volatile("v_cvt_pk_bf16_f32 %0, %1, %2" : "=v"(r) : "v"(lo), "v"(hi)); return r; }
; __device__ __forceinline__ float bf_lo(unsigned w) { return __uint_as_float(w << 16); }
; __device__ __forceinline__ float bf_hi(unsigned w) { return __uint_as_float(w & 0xffff0000u); }
;     __device__ __forceinline__ void operator()(f32x4 (&acc)[2][2][4][2], const Unit& u, int wr, int wc, int fr, int fq) const {
;     ...
;             for (int m = 0; m < 4; ++m) { const int row = row0 + ai * HALF + m * 16; float s = 0.f;
; #pragma unroll
;                 for (int bj = 0; bj < 2; ++bj) { const size_t o2 = (size_t)row * 1024 + col0 + bj * HALF; const u32x4 p = pre[ai][m][bj]; const f32x4 a0 = acc[ai][bj][m][0], a1 = acc[ai][bj][m][1];
;                     f32x4 o0, o1; o0[0] = bf_lo(p.x) + a0[0] * alpha; o0[1] = bf_hi(p.x) + a0[1] * alpha; o0[2] = bf_lo(p.y) + a0[2] * alpha; o0[3] = bf_hi(p.y) + a0[3] * alpha;
;                     o1[0] = bf_lo(p.z) + a1[0] * alpha; o1[1] = bf_hi(p.z) + a1[1] * alpha; o1[2] = bf_lo(p.w) + a1[2] * alpha; o1[3] = bf_hi(p.w) + a1[3] * alpha;
;                     s += ((o0[0] * o0[0] + o0[1] * o0[1]) + (o0[2] * o0[2] + o0[3] * o0[3])) + ((o1[0] * o1[0] + o1[1] * o1[1]) + (o1[2] * o1[2] + o1[3] * o1[3]));
;                     u32x4 w; w.x = cvt_pk_bf16(o0[0], o0[1]); w.y = cvt_pk_bf16(o0[2], o0[3]); w.z = cvt_pk_bf16(o1[0], o1[1]); w.w = cvt_pk_bf16(o1[2], o1[3]);
;                     *(u32x4*)hb_at(u, ai, m, bj, wr, wc, fr, fq) = w;
;                     if (out) { *(f32x4*)(out + o2) = o0; *(f32x4*)(out + o2 + 4) = o1; } }
;                 s += __shfl_xor(s, 16); s += __shfl_xor(s, 32);
;                 if (ssq && fq == 0) atomicAdd(ssq + row, s); }
.LBB0_241:
	s_or_b64 exec, exec, s[72:73]
	s_waitcnt vmcnt(15)
	v_lshlrev_b32_e32 v32, 16, v140
	v_fmac_f32_e32 v32, 0.5, v28
	v_and_b32_e32 v28, 0xffff0000, v140
	v_fmac_f32_e32 v28, 0.5, v29
	v_lshlrev_b32_e32 v29, 16, v141
	v_fmac_f32_e32 v29, 0.5, v30
	v_and_b32_e32 v30, 0xffff0000, v141
	v_fmac_f32_e32 v30, 0.5, v31
	v_lshlrev_b32_e32 v31, 16, v142
	s_waitcnt lgkmcnt(0)
	v_and_b32_e32 v33, 0xffff0000, v142
	v_fmac_f32_e32 v31, 0.5, v24
	v_fmac_f32_e32 v33, 0.5, v25
	v_and_b32_e32 v35, 0xffff0000, v143
	v_mul_f32_e32 v24, v28, v28
	v_mul_f32_e32 v25, v30, v30
	v_lshlrev_b32_e32 v34, 16, v143
	v_fmac_f32_e32 v35, 0.5, v27
	v_fmac_f32_e32 v24, v32, v32
	v_fmac_f32_e32 v25, v29, v29
	v_fmac_f32_e32 v34, 0.5, v26
	v_add_f32_e32 v24, v24, v25
	v_mul_f32_e32 v25, v33, v33
	v_mul_f32_e32 v26, v35, v35
	v_fmac_f32_e32 v25, v31, v31
	v_fmac_f32_e32 v26, v34, v34
	v_add_f32_e32 v25, v25, v26
	v_add_f32_e32 v36, v24, v25
	v_cvt_pk_bf16_f32 v24, v32, v28
	s_waitcnt vmcnt(14)
	v_lshlrev_b32_e32 v28, 16, v136
	v_fmac_f32_e32 v28, 0.5, v20
	v_and_b32_e32 v20, 0xffff0000, v136
	v_fmac_f32_e32 v20, 0.5, v21
	v_lshlrev_b32_e32 v21, 16, v137
	v_fmac_f32_e32 v21, 0.5, v22
	v_and_b32_e32 v22, 0xffff0000, v137
	v_cvt_pk_bf16_f32 v25, v29, v30
	v_fmac_f32_e32 v22, 0.5, v23
	v_lshlrev_b32_e32 v23, 16, v138
	v_and_b32_e32 v29, 0xffff0000, v138
	v_cvt_pk_bf16_f32 v26, v31, v33
	v_fmac_f32_e32 v23, 0.5, v16
	v_fmac_f32_e32 v29, 0.5, v17
	v_and_b32_e32 v31, 0xffff0000, v139
	v_mul_f32_e32 v16, v20, v20
	v_mul_f32_e32 v17, v22, v22
	v_lshlrev_b32_e32 v30, 16, v139
	v_fmac_f32_e32 v31, 0.5, v19
	v_fmac_f32_e32 v16, v28, v28
	v_fmac_f32_e32 v17, v21, v21
	v_fmac_f32_e32 v30, 0.5, v18
	v_add_f32_e32 v16, v16, v17
	v_mul_f32_e32 v17, v29, v29
	v_mul_f32_e32 v18, v31, v31
	v_fmac_f32_e32 v17, v23, v23
	v_fmac_f32_e32 v18, v30, v30
	v_add_f32_e32 v17, v17, v18
	v_add_f32_e32 v16, v16, v17
	v_add_f32_e32 v32, v36, v16
	ds_bpermute_b32 v33, v116, v32
	v_lshl_add_u64 v[16:17], s[70:71], 0, v[194:195]
	v_cvt_pk_bf16_f32 v27, v34, v35
	global_store_dwordx4 v[16:17], v[24:27], off sc1
	v_cvt_pk_bf16_f32 v18, v28, v20
	s_waitcnt lgkmcnt(0)
	v_add_f32_e32 v16, v32, v33
	ds_bpermute_b32 v17, v117, v16
	v_cvt_pk_bf16_f32 v19, v21, v22
	v_cvt_pk_bf16_f32 v20, v23, v29
	v_lshl_add_u64 v[22:23], s[68:69], 0, v[194:195]
	v_cvt_pk_bf16_f32 v21, v30, v31
	global_store_dwordx4 v[22:23], v[18:21], off sc1
	s_and_saveexec_b64 s[72:73], s[2:3]
	s_cbranch_execz .LBB0_243
	v_lshl_add_u64 v[18:19], v[208:209], 2, s[10:11]
	s_waitcnt lgkmcnt(0)
	v_add_f32_e32 v16, v16, v17
	global_atomic_add_f32 v[18:19], v16, off offset:640
.LBB0_243:
	s_or_b64 exec, exec, s[72:73]
	s_waitcnt vmcnt(15)
	v_lshlrev_b32_e32 v16, 16, v124
	v_fmac_f32_e32 v16, 0.5, v12
	v_and_b32_e32 v12, 0xffff0000, v124
	v_fmac_f32_e32 v12, 0.5, v13
	v_lshlrev_b32_e32 v13, 16, v125
	v_fmac_f32_e32 v13, 0.5, v14
	v_and_b32_e32 v14, 0xffff0000, v125
	v_fmac_f32_e32 v14, 0.5, v15
	v_lshlrev_b32_e32 v15, 16, v126
	s_waitcnt lgkmcnt(0)
	v_and_b32_e32 v17, 0xffff0000, v126
	v_fmac_f32_e32 v15, 0.5, v8
	v_fmac_f32_e32 v17, 0.5, v9
	v_and_b32_e32 v19, 0xffff0000, v127
	v_mul_f32_e32 v8, v12, v12
	v_mul_f32_e32 v9, v14, v14
	v_lshlrev_b32_e32 v18, 16, v127
	v_fmac_f32_e32 v19, 0.5, v11
	v_fmac_f32_e32 v8, v16, v16
	v_fmac_f32_e32 v9, v13, v13
	v_fmac_f32_e32 v18, 0.5, v10
	v_add_f32_e32 v8, v8, v9
	v_mul_f32_e32 v9, v17, v17
	v_mul_f32_e32 v10, v19, v19
	v_fmac_f32_e32 v9, v15, v15
	v_fmac_f32_e32 v10, v18, v18
	v_add_f32_e32 v9, v9, v10
	v_add_f32_e32 v20, v8, v9
	v_cvt_pk_bf16_f32 v8, v16, v12
	s_waitcnt vmcnt(14)
	v_lshlrev_b32_e32 v12, 16, v112
	v_fmac_f32_e32 v12, 0.5, v4
	v_and_b32_e32 v4, 0xffff0000, v112
	v_fmac_f32_e32 v4, 0.5, v5
	v_lshlrev_b32_e32 v5, 16, v113
	v_fmac_f32_e32 v5, 0.5, v6
	v_and_b32_e32 v6, 0xffff0000, v113
	v_cvt_pk_bf16_f32 v9, v13, v14
	v_fmac_f32_e32 v6, 0.5, v7
	v_lshlrev_b32_e32 v7, 16, v114
	v_and_b32_e32 v13, 0xffff0000, v114
	v_cvt_pk_bf16_f32 v10, v15, v17
	v_fmac_f32_e32 v7, 0.5, v0
	v_fmac_f32_e32 v13, 0.5, v1
	v_and_b32_e32 v15, 0xffff0000, v115
	v_mul_f32_e32 v0, v4, v4
	v_mul_f32_e32 v1, v6, v6
	v_lshlrev_b32_e32 v14, 16, v115
	v_fmac_f32_e32 v15, 0.5, v3
	v_fmac_f32_e32 v0, v12, v12
	v_fmac_f32_e32 v1, v5, v5
	v_fmac_f32_e32 v14, 0.5, v2
	v_add_f32_e32 v0, v0, v1
	v_mul_f32_e32 v1, v13, v13
	v_mul_f32_e32 v2, v15, v15
	v_fmac_f32_e32 v1, v7, v7
	v_fmac_f32_e32 v2, v14, v14
	v_add_f32_e32 v1, v1, v2
	v_add_f32_e32 v0, v0, v1
	v_add_f32_e32 v16, v20, v0
	ds_bpermute_b32 v17, v116, v16
	v_lshl_add_u64 v[0:1], s[70:71], 0, v[186:187]
	v_cvt_pk_bf16_f32 v11, v18, v19
	global_store_dwordx4 v[0:1], v[8:11], off sc1
	v_cvt_pk_bf16_f32 v2, v12, v4
	s_waitcnt lgkmcnt(0)
	v_add_f32_e32 v0, v16, v17
	ds_bpermute_b32 v1, v117, v0
	v_cvt_pk_bf16_f32 v3, v5, v6
	v_cvt_pk_bf16_f32 v4, v7, v13
	v_lshl_add_u64 v[6:7], s[68:69], 0, v[186:187]
	v_cvt_pk_bf16_f32 v5, v14, v15
	global_store_dwordx4 v[6:7], v[2:5], off sc1
	s_and_saveexec_b64 s[68:69], s[2:3]
	s_cbranch_execz .LBB0_245
	v_lshl_add_u64 v[2:3], v[208:209], 2, s[10:11]
	s_waitcnt lgkmcnt(0)
	v_add_f32_e32 v0, v0, v1
	global_atomic_add_f32 v[2:3], v0, off offset:704

;     __device__ static __forceinline__ float ub(unsigned w, int k) { return (float)((w >> (8 * k)) & 0xffu); }
;     __device__ __forceinline__ void operator()(f32x4 (&acc)[2][2][4][2], const Unit& u, int wr, int wc, int fr, int fq) const {
;     ...
;             for (int ai = 0; ai < 2; ++ai)
; #pragma unroll
;                 for (int m = 0; m < 4; ++m)
; #pragma unroll
;                     for (int bj = 0; bj < 2; ++bj) { const u32x4 gq = gw[ai][m]; u32x2 g; g.x = bj ? gq.z : gq.x; g.y = bj ? gq.w : gq.y; f32x4& a0 = acc[ai][bj][m][0]; f32x4& a1 = acc[ai][bj][m][1];
;                         a0[0] *= ub(g.x, 0) * q; a0[1] *= ub(g.x, 1) * q; a0[2] *= ub(g.x, 2) * q; a0[3] *= ub(g.x, 3) * q; a1[0] *= ub(g.y, 0) * q; a1[1] *= ub(g.y, 1) * q; a1[2] *= ub(g.y, 2) * q; a1[3] *= ub(g.y, 3) * q;
;                         asm volatile("" : "+v"(a0), "+v"(a1)); }
.Lnoal_3:
	s_waitcnt vmcnt(7)
	v_cvt_f32_ubyte3_e32 v203, v156
	v_cvt_f32_ubyte2_e32 v202, v156
	v_cvt_f32_ubyte1_e32 v205, v156
	v_cvt_f32_ubyte0_e32 v204, v156
	v_pk_mul_f32 v[204:205], v[204:205], s[58:59] op_sel_hi:[1,0]
	v_pk_mul_f32 v[202:203], v[202:203], s[58:59] op_sel_hi:[1,0]
	v_pk_mul_f32 v[124:125], v[124:125], v[204:205]
	v_pk_mul_f32 v[126:127], v[126:127], v[202:203]
	v_cvt_f32_ubyte3_e32 v203, v157
	v_cvt_f32_ubyte2_e32 v202, v157
	v_cvt_f32_ubyte1_e32 v205, v157
	v_cvt_f32_ubyte0_e32 v204, v157
	v_pk_mul_f32 v[156:157], v[204:205], s[58:59] op_sel_hi:[1,0]
	v_pk_mul_f32 v[202:203], v[202:203], s[58:59] op_sel_hi:[1,0]
	v_pk_mul_f32 v[120:121], v[120:121], v[156:157]
	v_pk_mul_f32 v[122:123], v[122:123], v[202:203]
	v_cvt_f32_ubyte3_e32 v157, v158
	v_cvt_f32_ubyte2_e32 v156, v158
	v_cvt_f32_ubyte1_e32 v203, v158
	v_cvt_f32_ubyte0_e32 v202, v158
	v_pk_mul_f32 v[202:203], v[202:203], s[58:59] op_sel_hi:[1,0]
	v_pk_mul_f32 v[156:157], v[156:157], s[58:59] op_sel_hi:[1,0]
	v_pk_mul_f32 v[116:117], v[116:117], v[202:203]
	v_pk_mul_f32 v[118:119], v[118:119], v[156:157]
	v_cvt_f32_ubyte3_e32 v157, v159
	v_cvt_f32_ubyte2_e32 v156, v159
	v_cvt_f32_ubyte1_e32 v203, v159
	v_cvt_f32_ubyte0_e32 v202, v159
	v_pk_mul_f32 v[158:159], v[202:203], s[58:59] op_sel_hi:[1,0]
	v_pk_mul_f32 v[156:157], v[156:157], s[58:59] op_sel_hi:[1,0]
	v_pk_mul_f32 v[112:113], v[112:113], v[158:159]
	v_pk_mul_f32 v[114:115], v[114:115], v[156:157]
	s_waitcnt vmcnt(6)
	v_cvt_f32_ubyte3_e32 v157, v152
	v_cvt_f32_ubyte2_e32 v156, v152
	v_cvt_f32_ubyte1_e32 v159, v152
	v_cvt_f32_ubyte0_e32 v158, v152
	v_pk_mul_f32 v[158:159], v[158:159], s[58:59] op_sel_hi:[1,0]
	v_pk_mul_f32 v[156:157], v[156:157], s[58:59] op_sel_hi:[1,0]
	v_pk_mul_f32 v[108:109], v[108:109], v[158:159]
	v_pk_mul_f32 v[110:111], v[110:111], v[156:157]
	v_cvt_f32_ubyte3_e32 v157, v153
	v_cvt_f32_ubyte2_e32 v156, v153
	v_cvt_f32_ubyte1_e32 v159, v153
	v_cvt_f32_ubyte0_e32 v158, v153
	v_pk_mul_f32 v[152:153], v[158:159], s[58:59] op_sel_hi:[1,0]
	v_pk_mul_f32 v[156:157], v[156:157], s[58:59] op_sel_hi:[1,0]
	v_pk_mul_f32 v[104:105], v[104:105], v[152:153]
	v_pk_mul_f32 v[106:107], v[106:107], v[156:157]
	v_cvt_f32_ubyte3_e32 v153, v154
	v_cvt_f32_ubyte2_e32 v152, v154
	v_cvt_f32_ubyte1_e32 v157, v154
	v_cvt_f32_ubyte0_e32 v156, v154
	v_pk_mul_f32 v[156:157], v[156:157], s[58:59] op_sel_hi:[1,0]
	v_pk_mul_f32 v[152:153], v[152:153], s[58:59] op_sel_hi:[1,0]
	v_pk_mul_f32 v[100:101], v[100:101], v[156:157]
	v_pk_mul_f32 v[102:103], v[102:103], v[152:153]
	v_cvt_f32_ubyte3_e32 v153, v155
	v_cvt_f32_ubyte2_e32 v152, v155
	v_cvt_f32_ubyte1_e32 v157, v155
	v_cvt_f32_ubyte0_e32 v156, v155
	v_pk_mul_f32 v[154:155], v[156:157], s[58:59] op_sel_hi:[1,0]
	v_pk_mul_f32 v[152:153], v[152:153], s[58:59] op_sel_hi:[1,0]
	v_pk_mul_f32 v[92:93], v[92:93], v[154:155]
	v_pk_mul_f32 v[94:95], v[94:95], v[152:153]
	s_waitcnt vmcnt(5)
	v_cvt_f32_ubyte3_e32 v153, v148
	v_cvt_f32_ubyte2_e32 v152, v148
	v_cvt_f32_ubyte1_e32 v155, v148
	v_cvt_f32_ubyte0_e32 v154, v148
	v_pk_mul_f32 v[154:155], v[154:155], s[58:59] op_sel_hi:[1,0]
	v_pk_mul_f32 v[152:153], v[152:153], s[58:59] op_sel_hi:[1,0]
	v_pk_mul_f32 v[96:97], v[96:97], v[154:155]
	v_pk_mul_f32 v[98:99], v[98:99], v[152:153]
	v_cvt_f32_ubyte3_e32 v153, v149
	v_cvt_f32_ubyte2_e32 v152, v149
	v_cvt_f32_ubyte1_e32 v155, v149
	v_cvt_f32_ubyte0_e32 v154, v149
	v_pk_mul_f32 v[148:149], v[154:155], s[58:59] op_sel_hi:[1,0]
	v_pk_mul_f32 v[152:153], v[152:153], s[58:59] op_sel_hi:[1,0]
	v_pk_mul_f32 v[88:89], v[88:89], v[148:149]
	v_pk_mul_f32 v[90:91], v[90:91], v[152:153]
	v_cvt_f32_ubyte3_e32 v149, v150
	v_cvt_f32_ubyte2_e32 v148, v150
	v_cvt_f32_ubyte1_e32 v153, v150
	v_cvt_f32_ubyte0_e32 v152, v150
	v_pk_mul_f32 v[152:153], v[152:153], s[58:59] op_sel_hi:[1,0]
	v_pk_mul_f32 v[148:149], v[148:149], s[58:59] op_sel_hi:[1,0]
	v_pk_mul_f32 v[84:85], v[84:85], v[152:153]
	v_pk_mul_f32 v[86:87], v[86:87], v[148:149]
	v_cvt_f32_ubyte3_e32 v149, v151
	v_cvt_f32_ubyte2_e32 v148, v151
	v_cvt_f32_ubyte1_e32 v153, v151
	v_cvt_f32_ubyte0_e32 v152, v151
	v_pk_mul_f32 v[150:151], v[152:153], s[58:59] op_sel_hi:[1,0]
	v_pk_mul_f32 v[148:149], v[148:149], s[58:59] op_sel_hi:[1,0]
	v_pk_mul_f32 v[76:77], v[76:77], v[150:151]
	v_pk_mul_f32 v[78:79], v[78:79], v[148:149]
	s_waitcnt vmcnt(4)
	v_cvt_f32_ubyte3_e32 v149, v144
	v_cvt_f32_ubyte2_e32 v148, v144
	v_cvt_f32_ubyte1_e32 v151, v144
	v_cvt_f32_ubyte0_e32 v150, v144
	v_pk_mul_f32 v[150:151], v[150:151], s[58:59] op_sel_hi:[1,0]
	v_pk_mul_f32 v[148:149], v[148:149], s[58:59] op_sel_hi:[1,0]
	v_pk_mul_f32 v[80:81], v[80:81], v[150:151]
	v_pk_mul_f32 v[82:83], v[82:83], v[148:149]
	v_cvt_f32_ubyte3_e32 v149, v145
	v_cvt_f32_ubyte2_e32 v148, v145
	v_cvt_f32_ubyte1_e32 v151, v145
	v_cvt_f32_ubyte0_e32 v150, v145
	v_pk_mul_f32 v[144:145], v[150:151], s[58:59] op_sel_hi:[1,0]
	v_pk_mul_f32 v[148:149], v[148:149], s[58:59] op_sel_hi:[1,0]
	v_pk_mul_f32 v[72:73], v[72:73], v[144:145]
	v_pk_mul_f32 v[74:75], v[74:75], v[148:149]
	v_cvt_f32_ubyte3_e32 v145, v146
	v_cvt_f32_ubyte2_e32 v144, v146
	v_cvt_f32_ubyte1_e32 v149, v146
	v_cvt_f32_ubyte0_e32 v148, v146
	v_pk_mul_f32 v[148:149], v[148:149], s[58:59] op_sel_hi:[1,0]
	v_pk_mul_f32 v[144:145], v[144:145], s[58:59] op_sel_hi:[1,0]
	v_pk_mul_f32 v[68:69], v[68:69], v[148:149]
	v_pk_mul_f32 v[70:71], v[70:71], v[144:145]
	v_cvt_f32_ubyte3_e32 v145, v147
	v_cvt_f32_ubyte2_e32 v144, v147
	v_cvt_f32_ubyte1_e32 v149, v147
	v_cvt_f32_ubyte0_e32 v148, v147
	v_pk_mul_f32 v[146:147], v[148:149], s[58:59] op_sel_hi:[1,0]
	v_pk_mul_f32 v[144:145], v[144:145], s[58:59] op_sel_hi:[1,0]
	v_pk_mul_f32 v[64:65], v[64:65], v[146:147]
	v_pk_mul_f32 v[66:67], v[66:67], v[144:145]
	s_waitcnt vmcnt(3)
;     __device__ static __forceinline__ float ub(unsigned w, int k) { return (float)((w >> (8 * k)) & 0xffu); }
;     __device__ __forceinline__ void operator()(f32x4 (&acc)[2][2][4][2], const Unit& u, int wr, int wc, int fr, int fq) const {
;     ...
;             for (int ai = 0; ai < 2; ++ai)
; #pragma unroll
;                 for (int m = 0; m < 4; ++m)
; #pragma unroll
;                     for (int bj = 0; bj < 2; ++bj) { const u32x4 gq = gw[ai][m]; u32x2 g; g.x = bj ? gq.z : gq.x; g.y = bj ? gq.w : gq.y; f32x4& a0 = acc[ai][bj][m][0]; f32x4& a1 = acc[ai][bj][m][1];
;                         a0[0] *= ub(g.x, 0) * q; a0[1] *= ub(g.x, 1) * q; a0[2] *= ub(g.x, 2) * q; a0[3] *= ub(g.x, 3) * q; a1[0] *= ub(g.y, 0) * q; a1[1] *= ub(g.y, 1) * q; a1[2] *= ub(g.y, 2) * q; a1[3] *= ub(g.y, 3) * q;
;                         asm volatile("" : "+v"(a0), "+v"(a1)); }
	v_cvt_f32_ubyte3_e32 v145, v140
	v_cvt_f32_ubyte2_e32 v144, v140
	v_cvt_f32_ubyte1_e32 v147, v140
	v_cvt_f32_ubyte0_e32 v146, v140
	v_pk_mul_f32 v[146:147], v[146:147], s[58:59] op_sel_hi:[1,0]
	v_pk_mul_f32 v[144:145], v[144:145], s[58:59] op_sel_hi:[1,0]
	v_pk_mul_f32 v[60:61], v[60:61], v[146:147]
	v_pk_mul_f32 v[62:63], v[62:63], v[144:145]
	v_cvt_f32_ubyte3_e32 v145, v141
	v_cvt_f32_ubyte2_e32 v144, v141
	v_cvt_f32_ubyte1_e32 v147, v141
	v_cvt_f32_ubyte0_e32 v146, v141
	v_pk_mul_f32 v[140:141], v[146:147], s[58:59] op_sel_hi:[1,0]
	v_pk_mul_f32 v[144:145], v[144:145], s[58:59] op_sel_hi:[1,0]
	v_pk_mul_f32 v[56:57], v[56:57], v[140:141]
	v_pk_mul_f32 v[58:59], v[58:59], v[144:145]
	v_cvt_f32_ubyte3_e32 v141, v142
	v_cvt_f32_ubyte2_e32 v140, v142
	v_cvt_f32_ubyte1_e32 v145, v142
	v_cvt_f32_ubyte0_e32 v144, v142
	v_pk_mul_f32 v[144:145], v[144:145], s[58:59] op_sel_hi:[1,0]
	v_pk_mul_f32 v[140:141], v[140:141], s[58:59] op_sel_hi:[1,0]
	v_pk_mul_f32 v[52:53], v[52:53], v[144:145]
	v_pk_mul_f32 v[54:55], v[54:55], v[140:141]
	v_cvt_f32_ubyte3_e32 v141, v143
	v_cvt_f32_ubyte2_e32 v140, v143
	v_cvt_f32_ubyte1_e32 v145, v143
	v_cvt_f32_ubyte0_e32 v144, v143
	v_pk_mul_f32 v[142:143], v[144:145], s[58:59] op_sel_hi:[1,0]
	v_pk_mul_f32 v[140:141], v[140:141], s[58:59] op_sel_hi:[1,0]
	v_pk_mul_f32 v[44:45], v[44:45], v[142:143]
	v_pk_mul_f32 v[46:47], v[46:47], v[140:141]
	s_waitcnt vmcnt(2)
	v_cvt_f32_ubyte3_e32 v141, v136
	v_cvt_f32_ubyte2_e32 v140, v136
	v_cvt_f32_ubyte1_e32 v143, v136
	v_cvt_f32_ubyte0_e32 v142, v136
	v_pk_mul_f32 v[142:143], v[142:143], s[58:59] op_sel_hi:[1,0]
	v_pk_mul_f32 v[140:141], v[140:141], s[58:59] op_sel_hi:[1,0]
	v_pk_mul_f32 v[48:49], v[48:49], v[142:143]
	v_pk_mul_f32 v[50:51], v[50:51], v[140:141]
	v_cvt_f32_ubyte3_e32 v141, v137
	v_cvt_f32_ubyte2_e32 v140, v137
	v_cvt_f32_ubyte1_e32 v143, v137
	v_cvt_f32_ubyte0_e32 v142, v137
	v_pk_mul_f32 v[136:137], v[142:143], s[58:59] op_sel_hi:[1,0]
	v_pk_mul_f32 v[140:141], v[140:141], s[58:59] op_sel_hi:[1,0]
	v_pk_mul_f32 v[40:41], v[40:41], v[136:137]
	v_pk_mul_f32 v[42:43], v[42:43], v[140:141]
	v_cvt_f32_ubyte3_e32 v137, v138
	v_cvt_f32_ubyte2_e32 v136, v138
	v_cvt_f32_ubyte1_e32 v141, v138
	v_cvt_f32_ubyte0_e32 v140, v138
	v_pk_mul_f32 v[140:141], v[140:141], s[58:59] op_sel_hi:[1,0]
	v_pk_mul_f32 v[136:137], v[136:137], s[58:59] op_sel_hi:[1,0]
	v_pk_mul_f32 v[36:37], v[36:37], v[140:141]
	v_pk_mul_f32 v[38:39], v[38:39], v[136:137]
	v_cvt_f32_ubyte3_e32 v137, v139
	v_cvt_f32_ubyte2_e32 v136, v139
	v_cvt_f32_ubyte1_e32 v141, v139
	v_cvt_f32_ubyte0_e32 v140, v139
	v_pk_mul_f32 v[138:139], v[140:141], s[58:59] op_sel_hi:[1,0]
	v_pk_mul_f32 v[136:137], v[136:137], s[58:59] op_sel_hi:[1,0]
	v_pk_mul_f32 v[28:29], v[28:29], v[138:139]
	v_pk_mul_f32 v[30:31], v[30:31], v[136:137]
	s_waitcnt vmcnt(0)
; __device__ __forceinline__ unsigned cvt_pk_bf16(float lo, float hi) { unsigned r; asm volatile("v_cvt_pk_bf16_f32 %0, %1, %2" : "=v"(r) : "v"(lo), "v"(hi)); return r; }
;     __device__ static __forceinline__ float ub(unsigned w, int k) { return (float)((w >> (8 * k)) & 0xffu); }
;     __device__ __forceinline__ void operator()(f32x4 (&acc)[2][2][4][2], const Unit& u, int wr, int wc, int fr, int fq) const {
;     ...
;             for (int ai = 0; ai < 2; ++ai)
; #pragma unroll
;                 for (int m = 0; m < 4; ++m)
; #pragma unroll
;                     for (int bj = 0; bj < 2; ++bj) { const u32x4 gq = gw[ai][m]; u32x2 g; g.x = bj ? gq.z : gq.x; g.y = bj ? gq.w : gq.y; f32x4& a0 = acc[ai][bj][m][0]; f32x4& a1 = acc[ai][bj][m][1];
;                         a0[0] *= ub(g.x, 0) * q; a0[1] *= ub(g.x, 1) * q; a0[2] *= ub(g.x, 2) * q; a0[3] *= ub(g.x, 3) * q; a1[0] *= ub(g.y, 0) * q; a1[1] *= ub(g.y, 1) * q; a1[2] *= ub(g.y, 2) * q; a1[3] *= ub(g.y, 3) * q;
;                         asm volatile("" : "+v"(a0), "+v"(a1)); }
;     ...
; #pragma unroll
;         for (int ai = 0; ai < 2; ++ai)
; #pragma unroll
;             for (int m = 0; m < 4; ++m)
; #pragma unroll
;                 for (int bj = 0; bj < 2; ++bj) { const f32x4 a0 = acc[ai][bj][m][0], a1 = acc[ai][bj][m][1];
;                     u32x4 w; w.x = cvt_pk_bf16(a0[0], a0[1]); w.y = cvt_pk_bf16(a0[2], a0[3]); w.z = cvt_pk_bf16(a1[0], a1[1]); w.w = cvt_pk_bf16(a1[2], a1[3]);
;                     *(u32x4*)mg_at(u, ai, m, bj, wr, wc, fr, fq) = w; }
	v_cvt_f32_ubyte3_e32 v137, v128
	v_cvt_f32_ubyte2_e32 v136, v128
	v_cvt_f32_ubyte1_e32 v139, v128
	v_cvt_f32_ubyte0_e32 v138, v128
	v_pk_mul_f32 v[138:139], v[138:139], s[58:59] op_sel_hi:[1,0]
	v_pk_mul_f32 v[136:137], v[136:137], s[58:59] op_sel_hi:[1,0]
	v_pk_mul_f32 v[32:33], v[32:33], v[138:139]
	v_pk_mul_f32 v[34:35], v[34:35], v[136:137]
	v_cvt_f32_ubyte3_e32 v137, v129
	v_cvt_f32_ubyte2_e32 v136, v129
	v_cvt_f32_ubyte1_e32 v139, v129
	v_cvt_f32_ubyte0_e32 v138, v129
	v_pk_mul_f32 v[128:129], v[138:139], s[58:59] op_sel_hi:[1,0]
	v_pk_mul_f32 v[136:137], v[136:137], s[58:59] op_sel_hi:[1,0]
	v_pk_mul_f32 v[24:25], v[24:25], v[128:129]
	v_pk_mul_f32 v[26:27], v[26:27], v[136:137]
	v_cvt_f32_ubyte3_e32 v129, v130
	v_cvt_f32_ubyte2_e32 v128, v130
	v_cvt_f32_ubyte1_e32 v137, v130
	v_cvt_f32_ubyte0_e32 v136, v130
	v_pk_mul_f32 v[136:137], v[136:137], s[58:59] op_sel_hi:[1,0]
	v_pk_mul_f32 v[128:129], v[128:129], s[58:59] op_sel_hi:[1,0]
	v_pk_mul_f32 v[20:21], v[20:21], v[136:137]
	v_pk_mul_f32 v[22:23], v[22:23], v[128:129]
	v_cvt_f32_ubyte3_e32 v129, v131
	v_cvt_f32_ubyte2_e32 v128, v131
	v_cvt_f32_ubyte1_e32 v137, v131
	v_cvt_f32_ubyte0_e32 v136, v131
	v_pk_mul_f32 v[130:131], v[136:137], s[58:59] op_sel_hi:[1,0]
	v_pk_mul_f32 v[128:129], v[128:129], s[58:59] op_sel_hi:[1,0]
	v_pk_mul_f32 v[12:13], v[12:13], v[130:131]
	v_pk_mul_f32 v[14:15], v[14:15], v[128:129]
	v_cvt_f32_ubyte3_e32 v129, v132
	v_cvt_f32_ubyte2_e32 v128, v132
	v_cvt_f32_ubyte1_e32 v131, v132
	v_cvt_f32_ubyte0_e32 v130, v132
	v_pk_mul_f32 v[130:131], v[130:131], s[58:59] op_sel_hi:[1,0]
	v_pk_mul_f32 v[128:129], v[128:129], s[58:59] op_sel_hi:[1,0]
	v_pk_mul_f32 v[16:17], v[16:17], v[130:131]
	v_pk_mul_f32 v[18:19], v[18:19], v[128:129]
	v_cvt_f32_ubyte3_e32 v129, v133
	v_cvt_f32_ubyte2_e32 v128, v133
	v_cvt_f32_ubyte1_e32 v131, v133
	v_cvt_f32_ubyte0_e32 v130, v133
	v_pk_mul_f32 v[130:131], v[130:131], s[58:59] op_sel_hi:[1,0]
	v_pk_mul_f32 v[128:129], v[128:129], s[58:59] op_sel_hi:[1,0]
	v_pk_mul_f32 v[8:9], v[8:9], v[130:131]
	v_pk_mul_f32 v[10:11], v[10:11], v[128:129]
	v_cvt_f32_ubyte3_e32 v129, v134
	v_cvt_f32_ubyte2_e32 v128, v134
	v_cvt_f32_ubyte1_e32 v131, v134
	v_cvt_f32_ubyte0_e32 v130, v134
	v_pk_mul_f32 v[130:131], v[130:131], s[58:59] op_sel_hi:[1,0]
	v_pk_mul_f32 v[128:129], v[128:129], s[58:59] op_sel_hi:[1,0]
	v_pk_mul_f32 v[4:5], v[4:5], v[130:131]
	v_pk_mul_f32 v[6:7], v[6:7], v[128:129]
	v_cvt_f32_ubyte3_e32 v129, v135
	v_cvt_f32_ubyte2_e32 v128, v135
	v_cvt_f32_ubyte1_e32 v131, v135
	v_cvt_f32_ubyte0_e32 v130, v135
	v_pk_mul_f32 v[130:131], v[130:131], s[58:59] op_sel_hi:[1,0]
	v_pk_mul_f32 v[128:129], v[128:129], s[58:59] op_sel_hi:[1,0]
	v_pk_mul_f32 v[0:1], v[0:1], v[130:131]
	v_pk_mul_f32 v[2:3], v[2:3], v[128:129]
	s_nop 0
	v_cvt_pk_bf16_f32 v124, v124, v125
	v_cvt_pk_bf16_f32 v125, v126, v127
	v_cvt_pk_bf16_f32 v126, v120, v121
	v_lshl_add_u64 v[120:121], s[66:67], 0, v[164:165]
	v_cvt_pk_bf16_f32 v127, v122, v123
	global_store_dwordx4 v[120:121], v[124:127], off sc1
	v_cvt_pk_bf16_f32 v116, v116, v117
	v_cvt_pk_bf16_f32 v117, v118, v119
	v_cvt_pk_bf16_f32 v118, v112, v113
	v_lshl_add_u64 v[112:113], s[68:69], 0, v[164:165]
	v_cvt_pk_bf16_f32 v119, v114, v115
	global_store_dwordx4 v[112:113], v[116:119], off sc1
	v_cvt_pk_bf16_f32 v108, v108, v109
	v_cvt_pk_bf16_f32 v109, v110, v111
	v_cvt_pk_bf16_f32 v110, v104, v105
	v_lshl_add_u64 v[104:105], s[66:67], 0, v[166:167]
	v_cvt_pk_bf16_f32 v111, v106, v107
	global_store_dwordx4 v[104:105], v[108:111], off sc1
	v_cvt_pk_bf16_f32 v100, v100, v101
	v_cvt_pk_bf16_f32 v101, v102, v103
	v_cvt_pk_bf16_f32 v102, v92, v93
	v_lshl_add_u64 v[92:93], s[68:69], 0, v[166:167]
	v_cvt_pk_bf16_f32 v103, v94, v95
	global_store_dwordx4 v[92:93], v[100:103], off sc1
	v_cvt_pk_bf16_f32 v92, v96, v97
	v_cvt_pk_bf16_f32 v93, v98, v99
	v_cvt_pk_bf16_f32 v94, v88, v89
	v_lshl_add_u64 v[88:89], s[66:67], 0, v[168:169]
	v_cvt_pk_bf16_f32 v95, v90, v91
	global_store_dwordx4 v[88:89], v[92:95], off sc1
	v_cvt_pk_bf16_f32 v84, v84, v85
	v_cvt_pk_bf16_f32 v85, v86, v87
	v_cvt_pk_bf16_f32 v86, v76, v77
	v_lshl_add_u64 v[76:77], s[68:69], 0, v[168:169]
	v_cvt_pk_bf16_f32 v87, v78, v79
	global_store_dwordx4 v[76:77], v[84:87], off sc1
	v_cvt_pk_bf16_f32 v76, v80, v81
	v_cvt_pk_bf16_f32 v77, v82, v83
	v_cvt_pk_bf16_f32 v78, v72, v73
	v_lshl_add_u64 v[72:73], s[66:67], 0, v[170:171]
	s_add_u32 s66, s6, s8
	s_addc_u32 s67, s7, s9
	s_or_b32 s0, s0, 5
	s_ashr_i32 s1, s0, 31
	s_lshl_b64 s[0:1], s[0:1], 14
	v_cvt_pk_bf16_f32 v79, v74, v75
	global_store_dwordx4 v[72:73], v[76:79], off sc1
	v_cvt_pk_bf16_f32 v68, v68, v69
	v_cvt_pk_bf16_f32 v69, v70, v71
	v_cvt_pk_bf16_f32 v70, v64, v65
	v_lshl_add_u64 v[64:65], s[68:69], 0, v[170:171]
	s_add_u32 s0, s6, s0
	v_cvt_pk_bf16_f32 v71, v66, v67
	global_store_dwordx4 v[64:65], v[68:71], off sc1
	v_cvt_pk_bf16_f32 v60, v60, v61
	v_cvt_pk_bf16_f32 v61, v62, v63
	v_cvt_pk_bf16_f32 v62, v56, v57
	v_lshl_add_u64 v[56:57], s[66:67], 0, v[164:165]
	s_addc_u32 s1, s7, s1
	v_cvt_pk_bf16_f32 v63, v58, v59
	global_store_dwordx4 v[56:57], v[60:63], off sc1
	v_cvt_pk_bf16_f32 v52, v52, v53
	v_cvt_pk_bf16_f32 v53, v54, v55
	v_cvt_pk_bf16_f32 v54, v44, v45
	v_lshl_add_u64 v[44:45], s[0:1], 0, v[164:165]
	v_cvt_pk_bf16_f32 v55, v46, v47
	global_store_dwordx4 v[44:45], v[52:55], off sc1
	v_cvt_pk_bf16_f32 v44, v48, v49
	v_cvt_pk_bf16_f32 v45, v50, v51
	v_cvt_pk_bf16_f32 v46, v40, v41
	v_lshl_add_u64 v[40:41], s[66:67], 0, v[166:167]
	v_cvt_pk_bf16_f32 v47, v42, v43
	global_store_dwordx4 v[40:41], v[44:47], off sc1
	v_cvt_pk_bf16_f32 v36, v36, v37
	v_cvt_pk_bf16_f32 v37, v38, v39
	v_cvt_pk_bf16_f32 v38, v28, v29
	v_lshl_add_u64 v[28:29], s[0:1], 0, v[166:167]
	v_cvt_pk_bf16_f32 v39, v30, v31
	global_store_dwordx4 v[28:29], v[36:39], off sc1
	v_cvt_pk_bf16_f32 v28, v32, v33
	v_cvt_pk_bf16_f32 v29, v34, v35
	v_cvt_pk_bf16_f32 v30, v24, v25
	v_lshl_add_u64 v[24:25], s[66:67], 0, v[168:169]
	v_cvt_pk_bf16_f32 v31, v26, v27
	global_store_dwordx4 v[24:25], v[28:31], off sc1
	v_cvt_pk_bf16_f32 v20, v20, v21
	v_cvt_pk_bf16_f32 v21, v22, v23
	v_cvt_pk_bf16_f32 v22, v12, v13
	v_lshl_add_u64 v[12:13], s[0:1], 0, v[168:169]
	v_cvt_pk_bf16_f32 v23, v14, v15
	global_store_dwordx4 v[12:13], v[20:23], off sc1
	v_cvt_pk_bf16_f32 v12, v16, v17
	v_cvt_pk_bf16_f32 v13, v18, v19
	v_cvt_pk_bf16_f32 v14, v8, v9
	v_lshl_add_u64 v[8:9], s[66:67], 0, v[170:171]
	v_cvt_pk_bf16_f32 v15, v10, v11
	global_store_dwordx4 v[8:9], v[12:15], off sc1
	v_cvt_pk_bf16_f32 v4, v4, v5
	v_cvt_pk_bf16_f32 v5, v6, v7
	v_cvt_pk_bf16_f32 v6, v0, v1
	v_lshl_add_u64 v[0:1], s[0:1], 0, v[170:171]
	s_mov_b64 s[0:1], -1
	s_and_b64 vcc, exec, s[2:3]
	v_cvt_pk_bf16_f32 v7, v2, v3
	global_store_dwordx4 v[0:1], v[4:7], off sc1
	s_cbranch_vccnz .LBB0_636
	s_andn2_b64 vcc, exec, s[54:55]
	s_cbranch_vccnz .LBB0_635
	s_barrier
	s_branch .LBB0_635

; __device__ __forceinline__ float bf_lo(unsigned w) { return __uint_as_float(w << 16); }
; __device__ __forceinline__ float bf_hi(unsigned w) { return __uint_as_float(w & 0xffff0000u); }
;     __device__ static __forceinline__ float ub(unsigned w, int k) { return (float)((w >> (8 * k)) & 0xffu); }
;     __device__ __forceinline__ void operator()(f32x4 (&acc)[2][2][4][2], const Unit& u, int wr, int wc, int fr, int fq) const {
;     ...
;                     for (int bj = 0; bj < 2; ++bj) { const u32x4 gq = gw[ai][m]; u32x2 g; g.x = bj ? gq.z : gq.x; g.y = bj ? gq.w : gq.y; const u32x4 o = ow[m][bj]; f32x4& a0 = acc[ai][bj][m][0]; f32x4& a1 = acc[ai][bj][m][1];
;                         a0[0] = a0[0] * (ub(g.x, 0) * q) + bf_lo(o.x); a0[1] = a0[1] * (ub(g.x, 1) * q) + bf_hi(o.x); a0[2] = a0[2] * (ub(g.x, 2) * q) + bf_lo(o.y); a0[3] = a0[3] * (ub(g.x, 3) * q) + bf_hi(o.y);
;                         a1[0] = a1[0] * (ub(g.y, 0) * q) + bf_lo(o.z); a1[1] = a1[1] * (ub(g.y, 1) * q) + bf_hi(o.z); a1[2] = a1[2] * (ub(g.y, 2) * q) + bf_lo(o.w); a1[3] = a1[3] * (ub(g.y, 3) * q) + bf_hi(o.w);
;                         asm volatile("" : "+v"(a0), "+v"(a1)); }
.Lnoal_4:
	s_waitcnt vmcnt(15)
	v_cvt_f32_ubyte3_e32 v229, v204
	v_cvt_f32_ubyte2_e32 v228, v204
	v_pk_mul_f32 v[228:229], v[228:229], s[10:11] op_sel_hi:[1,0]
	v_cvt_f32_ubyte1_e32 v217, v204
	v_cvt_f32_ubyte0_e32 v216, v204
	v_cvt_f32_ubyte1_e32 v231, v205
	v_cvt_f32_ubyte0_e32 v230, v205
	v_pk_mul_f32 v[216:217], v[216:217], s[10:11] op_sel_hi:[1,0]
	v_pk_mul_f32 v[230:231], v[230:231], s[10:11] op_sel_hi:[1,0]
	s_waitcnt vmcnt(7)
	v_lshlrev_b32_e32 v232, 16, v208
	v_and_b32_e32 v233, 0xffff0000, v208
	v_lshlrev_b32_e32 v208, 16, v209
	v_and_b32_e32 v209, 0xffff0000, v209
	v_pk_fma_f32 v[130:131], v[130:131], v[228:229], v[208:209]
	v_cvt_f32_ubyte3_e32 v209, v205
	v_cvt_f32_ubyte2_e32 v208, v205
	v_pk_mul_f32 v[204:205], v[208:209], s[10:11] op_sel_hi:[1,0]
	v_lshlrev_b32_e32 v208, 16, v211
	v_and_b32_e32 v209, 0xffff0000, v211
	v_pk_fma_f32 v[126:127], v[126:127], v[204:205], v[208:209]
	v_cvt_f32_ubyte1_e32 v205, v206
	v_cvt_f32_ubyte0_e32 v204, v206
	v_pk_mul_f32 v[204:205], v[204:205], s[10:11] op_sel_hi:[1,0]
	s_waitcnt vmcnt(6)
	v_lshlrev_b32_e32 v208, 16, v212
	v_and_b32_e32 v209, 0xffff0000, v212
	v_pk_fma_f32 v[120:121], v[120:121], v[204:205], v[208:209]
	v_cvt_f32_ubyte3_e32 v205, v206
	v_cvt_f32_ubyte2_e32 v204, v206
	v_pk_mul_f32 v[204:205], v[204:205], s[10:11] op_sel_hi:[1,0]
	v_lshlrev_b32_e32 v208, 16, v213
	v_and_b32_e32 v209, 0xffff0000, v213
	v_pk_fma_f32 v[122:123], v[122:123], v[204:205], v[208:209]
	v_cvt_f32_ubyte1_e32 v205, v207
	v_cvt_f32_ubyte0_e32 v204, v207
	v_pk_mul_f32 v[204:205], v[204:205], s[10:11] op_sel_hi:[1,0]
	v_lshlrev_b32_e32 v208, 16, v214
	v_and_b32_e32 v209, 0xffff0000, v214
	v_pk_fma_f32 v[116:117], v[116:117], v[204:205], v[208:209]
	v_cvt_f32_ubyte3_e32 v205, v207
	v_cvt_f32_ubyte2_e32 v204, v207
	v_pk_mul_f32 v[204:205], v[204:205], s[10:11] op_sel_hi:[1,0]
	v_lshlrev_b32_e32 v206, 16, v215
	v_and_b32_e32 v207, 0xffff0000, v215
	v_pk_fma_f32 v[118:119], v[118:119], v[204:205], v[206:207]
	v_cvt_f32_ubyte1_e32 v205, v164
	v_cvt_f32_ubyte0_e32 v204, v164
	v_pk_mul_f32 v[204:205], v[204:205], s[10:11] op_sel_hi:[1,0]
	s_waitcnt vmcnt(5)
	v_lshlrev_b32_e32 v206, 16, v220
	v_and_b32_e32 v207, 0xffff0000, v220
	v_pk_fma_f32 v[112:113], v[112:113], v[204:205], v[206:207]
	v_cvt_f32_ubyte3_e32 v205, v164
	v_cvt_f32_ubyte2_e32 v204, v164
	v_pk_mul_f32 v[204:205], v[204:205], s[10:11] op_sel_hi:[1,0]
	v_lshlrev_b32_e32 v206, 16, v221
	v_and_b32_e32 v207, 0xffff0000, v221
	v_pk_fma_f32 v[114:115], v[114:115], v[204:205], v[206:207]
	v_cvt_f32_ubyte1_e32 v205, v165
	v_cvt_f32_ubyte0_e32 v204, v165
	v_pk_mul_f32 v[204:205], v[204:205], s[10:11] op_sel_hi:[1,0]
	v_lshlrev_b32_e32 v206, 16, v222
	v_and_b32_e32 v207, 0xffff0000, v222
	v_pk_fma_f32 v[104:105], v[104:105], v[204:205], v[206:207]
	v_cvt_f32_ubyte3_e32 v205, v165
	v_cvt_f32_ubyte2_e32 v204, v165
	v_pk_mul_f32 v[164:165], v[204:205], s[10:11] op_sel_hi:[1,0]
	v_lshlrev_b32_e32 v204, 16, v223
	v_and_b32_e32 v205, 0xffff0000, v223
	v_pk_fma_f32 v[106:107], v[106:107], v[164:165], v[204:205]
	v_cvt_f32_ubyte1_e32 v165, v166
	v_cvt_f32_ubyte0_e32 v164, v166
	v_pk_mul_f32 v[164:165], v[164:165], s[10:11] op_sel_hi:[1,0]
	s_waitcnt vmcnt(4)
	v_lshlrev_b32_e32 v204, 16, v224
	v_and_b32_e32 v205, 0xffff0000, v224
	v_pk_fma_f32 v[100:101], v[100:101], v[164:165], v[204:205]
	v_cvt_f32_ubyte3_e32 v165, v166
	v_cvt_f32_ubyte2_e32 v164, v166
	v_pk_mul_f32 v[164:165], v[164:165], s[10:11] op_sel_hi:[1,0]
	v_lshlrev_b32_e32 v204, 16, v225
	v_and_b32_e32 v205, 0xffff0000, v225
	v_pk_fma_f32 v[102:103], v[102:103], v[164:165], v[204:205]
	v_cvt_f32_ubyte1_e32 v165, v167
	v_cvt_f32_ubyte0_e32 v164, v167
	v_pk_mul_f32 v[164:165], v[164:165], s[10:11] op_sel_hi:[1,0]
	v_lshlrev_b32_e32 v204, 16, v226
	v_and_b32_e32 v205, 0xffff0000, v226
	v_pk_fma_f32 v[96:97], v[96:97], v[164:165], v[204:205]
	v_cvt_f32_ubyte3_e32 v165, v167
	v_cvt_f32_ubyte2_e32 v164, v167
	v_pk_mul_f32 v[164:165], v[164:165], s[10:11] op_sel_hi:[1,0]
	v_lshlrev_b32_e32 v166, 16, v227
	v_and_b32_e32 v167, 0xffff0000, v227
	v_pk_fma_f32 v[98:99], v[98:99], v[164:165], v[166:167]
	v_cvt_f32_ubyte1_e32 v165, v152
	v_cvt_f32_ubyte0_e32 v164, v152
	v_pk_mul_f32 v[164:165], v[164:165], s[10:11] op_sel_hi:[1,0]
	s_waitcnt vmcnt(3)
	v_lshlrev_b32_e32 v166, 16, v168
	v_and_b32_e32 v167, 0xffff0000, v168
	v_pk_fma_f32 v[92:93], v[92:93], v[164:165], v[166:167]
	v_cvt_f32_ubyte3_e32 v165, v152
	v_cvt_f32_ubyte2_e32 v164, v152
	v_pk_mul_f32 v[164:165], v[164:165], s[10:11] op_sel_hi:[1,0]
	v_lshlrev_b32_e32 v166, 16, v169
	v_and_b32_e32 v167, 0xffff0000, v169
	v_pk_fma_f32 v[94:95], v[94:95], v[164:165], v[166:167]
	v_cvt_f32_ubyte1_e32 v165, v153
	v_cvt_f32_ubyte0_e32 v164, v153
	v_pk_mul_f32 v[164:165], v[164:165], s[10:11] op_sel_hi:[1,0]
	v_lshlrev_b32_e32 v166, 16, v170
	v_and_b32_e32 v167, 0xffff0000, v170
	v_pk_fma_f32 v[88:89], v[88:89], v[164:165], v[166:167]
	v_cvt_f32_ubyte3_e32 v165, v153
	v_cvt_f32_ubyte2_e32 v164, v153
	v_pk_mul_f32 v[152:153], v[164:165], s[10:11] op_sel_hi:[1,0]
	v_lshlrev_b32_e32 v164, 16, v171
	v_and_b32_e32 v165, 0xffff0000, v171
	v_pk_fma_f32 v[90:91], v[90:91], v[152:153], v[164:165]
	v_cvt_f32_ubyte1_e32 v153, v154
	v_cvt_f32_ubyte0_e32 v152, v154
	v_pk_mul_f32 v[152:153], v[152:153], s[10:11] op_sel_hi:[1,0]
	s_waitcnt vmcnt(2)
; __device__ __forceinline__ float bf_lo(unsigned w) { return __uint_as_float(w << 16); }
; __device__ __forceinline__ float bf_hi(unsigned w) { return __uint_as_float(w & 0xffff0000u); }
;     __device__ static __forceinline__ float ub(unsigned w, int k) { return (float)((w >> (8 * k)) & 0xffu); }
;     __device__ __forceinline__ void operator()(f32x4 (&acc)[2][2][4][2], const Unit& u, int wr, int wc, int fr, int fq) const {
;     ...
;             for (int ai = 0; ai < 2; ++ai) { u32x4 ow[4][2];
;                 asm volatile("" : "+v"(chain) : "v"(dep));
; #pragma unroll
;                 for (int m = 0; m < 4; ++m)
; #pragma unroll
;                     for (int bj = 0; bj < 2; ++bj) ow[m][bj] = *(const u32x4*)(mg_at(u, ai, m, bj, wr, wc, fr, fq) + (chain - row0));
; #pragma unroll
;                 for (int m = 0; m < 4; ++m)
; #pragma unroll
;                     for (int bj = 0; bj < 2; ++bj) { const u32x4 gq = gw[ai][m]; u32x2 g; g.x = bj ? gq.z : gq.x; g.y = bj ? gq.w : gq.y; const u32x4 o = ow[m][bj]; f32x4& a0 = acc[ai][bj][m][0]; f32x4& a1 = acc[ai][bj][m][1];
;                         a0[0] = a0[0] * (ub(g.x, 0) * q) + bf_lo(o.x); a0[1] = a0[1] * (ub(g.x, 1) * q) + bf_hi(o.x); a0[2] = a0[2] * (ub(g.x, 2) * q) + bf_lo(o.y); a0[3] = a0[3] * (ub(g.x, 3) * q) + bf_hi(o.y);
;                         a1[0] = a1[0] * (ub(g.y, 0) * q) + bf_lo(o.z); a1[1] = a1[1] * (ub(g.y, 1) * q) + bf_hi(o.z); a1[2] = a1[2] * (ub(g.y, 2) * q) + bf_lo(o.w); a1[3] = a1[3] * (ub(g.y, 3) * q) + bf_hi(o.w);
;                         asm volatile("" : "+v"(a0), "+v"(a1)); }
	v_lshlrev_b32_e32 v164, 16, v160
	v_and_b32_e32 v165, 0xffff0000, v160
	v_pk_fma_f32 v[84:85], v[84:85], v[152:153], v[164:165]
	v_cvt_f32_ubyte3_e32 v153, v154
	v_cvt_f32_ubyte2_e32 v152, v154
	v_pk_mul_f32 v[152:153], v[152:153], s[10:11] op_sel_hi:[1,0]
	v_lshlrev_b32_e32 v160, 16, v161
	v_and_b32_e32 v161, 0xffff0000, v161
	v_pk_fma_f32 v[86:87], v[86:87], v[152:153], v[160:161]
	v_cvt_f32_ubyte1_e32 v153, v155
	v_cvt_f32_ubyte0_e32 v152, v155
	v_pk_mul_f32 v[152:153], v[152:153], s[10:11] op_sel_hi:[1,0]
	v_lshlrev_b32_e32 v160, 16, v162
	v_and_b32_e32 v161, 0xffff0000, v162
	v_pk_fma_f32 v[80:81], v[80:81], v[152:153], v[160:161]
	v_cvt_f32_ubyte3_e32 v153, v155
	v_cvt_f32_ubyte2_e32 v152, v155
	v_pk_mul_f32 v[152:153], v[152:153], s[10:11] op_sel_hi:[1,0]
	v_lshlrev_b32_e32 v154, 16, v163
	v_and_b32_e32 v155, 0xffff0000, v163
	v_pk_fma_f32 v[82:83], v[82:83], v[152:153], v[154:155]
	v_cvt_f32_ubyte1_e32 v153, v144
	v_cvt_f32_ubyte0_e32 v152, v144
	v_pk_mul_f32 v[152:153], v[152:153], s[10:11] op_sel_hi:[1,0]
	s_waitcnt vmcnt(1)
	v_lshlrev_b32_e32 v154, 16, v156
	v_and_b32_e32 v155, 0xffff0000, v156
	v_pk_fma_f32 v[76:77], v[76:77], v[152:153], v[154:155]
	v_cvt_f32_ubyte3_e32 v153, v144
	v_cvt_f32_ubyte2_e32 v152, v144
	v_pk_mul_f32 v[152:153], v[152:153], s[10:11] op_sel_hi:[1,0]
	v_lshlrev_b32_e32 v154, 16, v157
	v_and_b32_e32 v155, 0xffff0000, v157
	v_pk_fma_f32 v[78:79], v[78:79], v[152:153], v[154:155]
	v_cvt_f32_ubyte1_e32 v153, v145
	v_cvt_f32_ubyte0_e32 v152, v145
	v_pk_mul_f32 v[152:153], v[152:153], s[10:11] op_sel_hi:[1,0]
	v_lshlrev_b32_e32 v154, 16, v158
	v_and_b32_e32 v155, 0xffff0000, v158
	v_pk_fma_f32 v[72:73], v[72:73], v[152:153], v[154:155]
	v_cvt_f32_ubyte3_e32 v153, v145
	v_cvt_f32_ubyte2_e32 v152, v145
	v_pk_mul_f32 v[144:145], v[152:153], s[10:11] op_sel_hi:[1,0]
	v_lshlrev_b32_e32 v152, 16, v159
	v_and_b32_e32 v153, 0xffff0000, v159
	v_pk_fma_f32 v[74:75], v[74:75], v[144:145], v[152:153]
	v_cvt_f32_ubyte1_e32 v145, v146
	v_cvt_f32_ubyte0_e32 v144, v146
	v_pk_mul_f32 v[144:145], v[144:145], s[10:11] op_sel_hi:[1,0]
	s_waitcnt vmcnt(0)
	v_lshlrev_b32_e32 v152, 16, v148
	v_and_b32_e32 v153, 0xffff0000, v148
	v_pk_fma_f32 v[68:69], v[68:69], v[144:145], v[152:153]
	v_cvt_f32_ubyte3_e32 v145, v146
	v_cvt_f32_ubyte2_e32 v144, v146
	v_pk_mul_f32 v[144:145], v[144:145], s[10:11] op_sel_hi:[1,0]
	v_lshlrev_b32_e32 v148, 16, v149
	v_and_b32_e32 v149, 0xffff0000, v149
	v_pk_fma_f32 v[70:71], v[70:71], v[144:145], v[148:149]
	v_cvt_f32_ubyte1_e32 v145, v147
	v_cvt_f32_ubyte0_e32 v144, v147
	v_pk_mul_f32 v[144:145], v[144:145], s[10:11] op_sel_hi:[1,0]
	v_lshlrev_b32_e32 v148, 16, v150
	v_and_b32_e32 v149, 0xffff0000, v150
	v_pk_fma_f32 v[64:65], v[64:65], v[144:145], v[148:149]
	v_cvt_f32_ubyte3_e32 v145, v147
	v_cvt_f32_ubyte2_e32 v144, v147
	v_lshlrev_b32_e32 v234, 16, v210
	v_and_b32_e32 v235, 0xffff0000, v210
	v_pk_mul_f32 v[144:145], v[144:145], s[10:11] op_sel_hi:[1,0]
	v_lshlrev_b32_e32 v146, 16, v151
	v_and_b32_e32 v147, 0xffff0000, v151
	v_pk_fma_f32 v[128:129], v[128:129], v[216:217], v[232:233]
	v_pk_fma_f32 v[124:125], v[124:125], v[230:231], v[234:235]
	v_pk_fma_f32 v[66:67], v[66:67], v[144:145], v[146:147]
	s_nop 0
	v_cvt_f32_ubyte1_e32 v209, v140
	v_cvt_f32_ubyte0_e32 v208, v140
	v_sub_u32_e32 v144, v236, v219
	v_ashrrev_i32_e32 v145, 31, v144
	v_lshl_add_u64 v[144:145], s[6:7], 0, v[144:145]
	v_lshl_add_u64 v[146:147], v[144:145], 0, v[176:177]
	v_lshl_add_u64 v[148:149], v[146:147], 0, s[68:69]
	global_load_dwordx4 v[160:163], v[148:149], off
	v_lshl_add_u64 v[146:147], v[146:147], 0, s[66:67]
	global_load_dwordx4 v[164:167], v[146:147], off
	v_lshl_add_u64 v[146:147], v[144:145], 0, v[178:179]
	v_lshl_add_u64 v[148:149], v[146:147], 0, s[68:69]
	global_load_dwordx4 v[168:171], v[148:149], off
	v_lshl_add_u64 v[146:147], v[146:147], 0, s[66:67]
	global_load_dwordx4 v[204:207], v[146:147], off
	v_lshl_add_u64 v[146:147], v[144:145], 0, v[180:181]
	v_lshl_add_u64 v[148:149], v[146:147], 0, s[68:69]
	v_lshl_add_u64 v[146:147], v[146:147], 0, s[66:67]
	global_load_dwordx4 v[156:159], v[148:149], off
	global_load_dwordx4 v[152:155], v[146:147], off
	v_lshl_add_u64 v[144:145], v[144:145], 0, v[182:183]
	v_lshl_add_u64 v[146:147], v[144:145], 0, s[68:69]
	v_lshl_add_u64 v[144:145], v[144:145], 0, s[66:67]
	global_load_dwordx4 v[148:151], v[146:147], off
	s_nop 0
	global_load_dwordx4 v[144:147], v[144:145], off
	v_pk_mul_f32 v[208:209], v[208:209], s[10:11] op_sel_hi:[1,0]
	s_waitcnt vmcnt(7)
	v_lshlrev_b32_e32 v210, 16, v160
	v_and_b32_e32 v211, 0xffff0000, v160
	v_pk_fma_f32 v[60:61], v[60:61], v[208:209], v[210:211]
	v_cvt_f32_ubyte3_e32 v209, v140
	v_cvt_f32_ubyte2_e32 v208, v140
	v_pk_mul_f32 v[208:209], v[208:209], s[10:11] op_sel_hi:[1,0]
	v_lshlrev_b32_e32 v160, 16, v161
	v_and_b32_e32 v161, 0xffff0000, v161
	v_pk_fma_f32 v[62:63], v[62:63], v[208:209], v[160:161]
	v_cvt_f32_ubyte1_e32 v161, v141
	v_cvt_f32_ubyte0_e32 v160, v141
	v_pk_mul_f32 v[160:161], v[160:161], s[10:11] op_sel_hi:[1,0]
	v_lshlrev_b32_e32 v208, 16, v162
	v_and_b32_e32 v209, 0xffff0000, v162
	v_pk_fma_f32 v[56:57], v[56:57], v[160:161], v[208:209]
	v_cvt_f32_ubyte3_e32 v161, v141
	v_cvt_f32_ubyte2_e32 v160, v141
	v_pk_mul_f32 v[140:141], v[160:161], s[10:11] op_sel_hi:[1,0]
	v_lshlrev_b32_e32 v160, 16, v163
	v_and_b32_e32 v161, 0xffff0000, v163
	v_pk_fma_f32 v[58:59], v[58:59], v[140:141], v[160:161]
	v_cvt_f32_ubyte1_e32 v141, v142
	v_cvt_f32_ubyte0_e32 v140, v142
	v_pk_mul_f32 v[140:141], v[140:141], s[10:11] op_sel_hi:[1,0]
	s_waitcnt vmcnt(6)
; __device__ __forceinline__ float bf_lo(unsigned w) { return __uint_as_float(w << 16); }
; __device__ __forceinline__ float bf_hi(unsigned w) { return __uint_as_float(w & 0xffff0000u); }
;     __device__ static __forceinline__ float ub(unsigned w, int k) { return (float)((w >> (8 * k)) & 0xffu); }
;     __device__ __forceinline__ void operator()(f32x4 (&acc)[2][2][4][2], const Unit& u, int wr, int wc, int fr, int fq) const {
;     ...
;                     for (int bj = 0; bj < 2; ++bj) { const u32x4 gq = gw[ai][m]; u32x2 g; g.x = bj ? gq.z : gq.x; g.y = bj ? gq.w : gq.y; const u32x4 o = ow[m][bj]; f32x4& a0 = acc[ai][bj][m][0]; f32x4& a1 = acc[ai][bj][m][1];
;                         a0[0] = a0[0] * (ub(g.x, 0) * q) + bf_lo(o.x); a0[1] = a0[1] * (ub(g.x, 1) * q) + bf_hi(o.x); a0[2] = a0[2] * (ub(g.x, 2) * q) + bf_lo(o.y); a0[3] = a0[3] * (ub(g.x, 3) * q) + bf_hi(o.y);
;                         a1[0] = a1[0] * (ub(g.y, 0) * q) + bf_lo(o.z); a1[1] = a1[1] * (ub(g.y, 1) * q) + bf_hi(o.z); a1[2] = a1[2] * (ub(g.y, 2) * q) + bf_lo(o.w); a1[3] = a1[3] * (ub(g.y, 3) * q) + bf_hi(o.w);
;                         asm volatile("" : "+v"(a0), "+v"(a1)); }
	v_lshlrev_b32_e32 v160, 16, v164
	v_and_b32_e32 v161, 0xffff0000, v164
	v_pk_fma_f32 v[52:53], v[52:53], v[140:141], v[160:161]
	v_cvt_f32_ubyte3_e32 v141, v142
	v_cvt_f32_ubyte2_e32 v140, v142
	v_pk_mul_f32 v[140:141], v[140:141], s[10:11] op_sel_hi:[1,0]
	v_lshlrev_b32_e32 v160, 16, v165
	v_and_b32_e32 v161, 0xffff0000, v165
	v_pk_fma_f32 v[54:55], v[54:55], v[140:141], v[160:161]
	v_cvt_f32_ubyte1_e32 v141, v143
	v_cvt_f32_ubyte0_e32 v140, v143
	v_pk_mul_f32 v[140:141], v[140:141], s[10:11] op_sel_hi:[1,0]
	v_lshlrev_b32_e32 v160, 16, v166
	v_and_b32_e32 v161, 0xffff0000, v166
	v_pk_fma_f32 v[48:49], v[48:49], v[140:141], v[160:161]
	v_cvt_f32_ubyte3_e32 v141, v143
	v_cvt_f32_ubyte2_e32 v140, v143
	v_pk_mul_f32 v[140:141], v[140:141], s[10:11] op_sel_hi:[1,0]
	v_lshlrev_b32_e32 v142, 16, v167
	v_and_b32_e32 v143, 0xffff0000, v167
	v_pk_fma_f32 v[50:51], v[50:51], v[140:141], v[142:143]
	v_cvt_f32_ubyte1_e32 v141, v136
	v_cvt_f32_ubyte0_e32 v140, v136
	v_pk_mul_f32 v[140:141], v[140:141], s[10:11] op_sel_hi:[1,0]
	s_waitcnt vmcnt(5)
	v_lshlrev_b32_e32 v142, 16, v168
	v_and_b32_e32 v143, 0xffff0000, v168
	v_pk_fma_f32 v[44:45], v[44:45], v[140:141], v[142:143]
	v_cvt_f32_ubyte3_e32 v141, v136
	v_cvt_f32_ubyte2_e32 v140, v136
	v_pk_mul_f32 v[140:141], v[140:141], s[10:11] op_sel_hi:[1,0]
	v_lshlrev_b32_e32 v142, 16, v169
	v_and_b32_e32 v143, 0xffff0000, v169
	v_pk_fma_f32 v[46:47], v[46:47], v[140:141], v[142:143]
	v_cvt_f32_ubyte1_e32 v141, v137
	v_cvt_f32_ubyte0_e32 v140, v137
	v_pk_mul_f32 v[140:141], v[140:141], s[10:11] op_sel_hi:[1,0]
	v_lshlrev_b32_e32 v142, 16, v170
	v_and_b32_e32 v143, 0xffff0000, v170
	v_pk_fma_f32 v[40:41], v[40:41], v[140:141], v[142:143]
	v_cvt_f32_ubyte3_e32 v141, v137
	v_cvt_f32_ubyte2_e32 v140, v137
	v_pk_mul_f32 v[136:137], v[140:141], s[10:11] op_sel_hi:[1,0]
	v_lshlrev_b32_e32 v140, 16, v171
	v_and_b32_e32 v141, 0xffff0000, v171
	v_pk_fma_f32 v[42:43], v[42:43], v[136:137], v[140:141]
	v_cvt_f32_ubyte1_e32 v137, v138
	v_cvt_f32_ubyte0_e32 v136, v138
	v_pk_mul_f32 v[136:137], v[136:137], s[10:11] op_sel_hi:[1,0]
	s_waitcnt vmcnt(4)
	v_lshlrev_b32_e32 v140, 16, v204
	v_and_b32_e32 v141, 0xffff0000, v204
	v_pk_fma_f32 v[36:37], v[36:37], v[136:137], v[140:141]
	v_cvt_f32_ubyte3_e32 v137, v138
	v_cvt_f32_ubyte2_e32 v136, v138
	v_pk_mul_f32 v[136:137], v[136:137], s[10:11] op_sel_hi:[1,0]
	v_lshlrev_b32_e32 v140, 16, v205
	v_and_b32_e32 v141, 0xffff0000, v205
	v_pk_fma_f32 v[38:39], v[38:39], v[136:137], v[140:141]
	v_cvt_f32_ubyte1_e32 v137, v139
	v_cvt_f32_ubyte0_e32 v136, v139
	v_pk_mul_f32 v[136:137], v[136:137], s[10:11] op_sel_hi:[1,0]
	v_lshlrev_b32_e32 v140, 16, v206
	v_and_b32_e32 v141, 0xffff0000, v206
	v_pk_fma_f32 v[32:33], v[32:33], v[136:137], v[140:141]
	v_cvt_f32_ubyte3_e32 v137, v139
	v_cvt_f32_ubyte2_e32 v136, v139
	v_pk_mul_f32 v[136:137], v[136:137], s[10:11] op_sel_hi:[1,0]
	v_lshlrev_b32_e32 v138, 16, v207
	v_and_b32_e32 v139, 0xffff0000, v207
	v_pk_fma_f32 v[34:35], v[34:35], v[136:137], v[138:139]
	v_cvt_f32_ubyte1_e32 v137, v132
	v_cvt_f32_ubyte0_e32 v136, v132
	v_pk_mul_f32 v[136:137], v[136:137], s[10:11] op_sel_hi:[1,0]
	s_waitcnt vmcnt(3)
	v_lshlrev_b32_e32 v138, 16, v156
	v_and_b32_e32 v139, 0xffff0000, v156
	v_pk_fma_f32 v[28:29], v[28:29], v[136:137], v[138:139]
	v_cvt_f32_ubyte3_e32 v137, v132
	v_cvt_f32_ubyte2_e32 v136, v132
	v_pk_mul_f32 v[136:137], v[136:137], s[10:11] op_sel_hi:[1,0]
	v_lshlrev_b32_e32 v138, 16, v157
	v_and_b32_e32 v139, 0xffff0000, v157
	v_pk_fma_f32 v[30:31], v[30:31], v[136:137], v[138:139]
	v_cvt_f32_ubyte1_e32 v137, v133
	v_cvt_f32_ubyte0_e32 v136, v133
	v_pk_mul_f32 v[136:137], v[136:137], s[10:11] op_sel_hi:[1,0]
	v_lshlrev_b32_e32 v138, 16, v158
	v_and_b32_e32 v139, 0xffff0000, v158
	v_pk_fma_f32 v[24:25], v[24:25], v[136:137], v[138:139]
	v_cvt_f32_ubyte3_e32 v137, v133
	v_cvt_f32_ubyte2_e32 v136, v133
	v_pk_mul_f32 v[132:133], v[136:137], s[10:11] op_sel_hi:[1,0]
	v_lshlrev_b32_e32 v136, 16, v159
	v_and_b32_e32 v137, 0xffff0000, v159
	v_pk_fma_f32 v[26:27], v[26:27], v[132:133], v[136:137]
	v_cvt_f32_ubyte1_e32 v133, v134
	v_cvt_f32_ubyte0_e32 v132, v134
	v_pk_mul_f32 v[132:133], v[132:133], s[10:11] op_sel_hi:[1,0]
	s_waitcnt vmcnt(2)
	v_lshlrev_b32_e32 v136, 16, v152
	v_and_b32_e32 v137, 0xffff0000, v152
	v_pk_fma_f32 v[20:21], v[20:21], v[132:133], v[136:137]
	v_cvt_f32_ubyte3_e32 v133, v134
	v_cvt_f32_ubyte2_e32 v132, v134
	v_pk_mul_f32 v[132:133], v[132:133], s[10:11] op_sel_hi:[1,0]
	v_lshlrev_b32_e32 v136, 16, v153
	v_and_b32_e32 v137, 0xffff0000, v153
	v_pk_fma_f32 v[22:23], v[22:23], v[132:133], v[136:137]
	v_cvt_f32_ubyte1_e32 v133, v135
	v_cvt_f32_ubyte0_e32 v132, v135
	v_pk_mul_f32 v[132:133], v[132:133], s[10:11] op_sel_hi:[1,0]
	v_lshlrev_b32_e32 v136, 16, v154
	v_and_b32_e32 v137, 0xffff0000, v154
	v_pk_fma_f32 v[16:17], v[16:17], v[132:133], v[136:137]
	v_cvt_f32_ubyte3_e32 v133, v135
	v_cvt_f32_ubyte2_e32 v132, v135
	v_pk_mul_f32 v[132:133], v[132:133], s[10:11] op_sel_hi:[1,0]
	v_lshlrev_b32_e32 v134, 16, v155
	v_and_b32_e32 v135, 0xffff0000, v155
	v_pk_fma_f32 v[18:19], v[18:19], v[132:133], v[134:135]
	v_cvt_f32_ubyte1_e32 v133, v108
	v_cvt_f32_ubyte0_e32 v132, v108
	v_pk_mul_f32 v[132:133], v[132:133], s[10:11] op_sel_hi:[1,0]
	s_waitcnt vmcnt(1)
; __device__ __forceinline__ unsigned cvt_pk_bf16(float lo, float hi) { unsigned r; asm volatile("v_cvt_pk_bf16_f32 %0, %1, %2" : "=v"(r) : "v"(lo), "v"(hi)); return r; }
; __device__ __forceinline__ float bf_lo(unsigned w) { return __uint_as_float(w << 16); }
; __device__ __forceinline__ float bf_hi(unsigned w) { return __uint_as_float(w & 0xffff0000u); }
;     __device__ static __forceinline__ float ub(unsigned w, int k) { return (float)((w >> (8 * k)) & 0xffu); }
;     __device__ __forceinline__ void operator()(f32x4 (&acc)[2][2][4][2], const Unit& u, int wr, int wc, int fr, int fq) const {
;     ...
;                     for (int bj = 0; bj < 2; ++bj) { const u32x4 gq = gw[ai][m]; u32x2 g; g.x = bj ? gq.z : gq.x; g.y = bj ? gq.w : gq.y; const u32x4 o = ow[m][bj]; f32x4& a0 = acc[ai][bj][m][0]; f32x4& a1 = acc[ai][bj][m][1];
;                         a0[0] = a0[0] * (ub(g.x, 0) * q) + bf_lo(o.x); a0[1] = a0[1] * (ub(g.x, 1) * q) + bf_hi(o.x); a0[2] = a0[2] * (ub(g.x, 2) * q) + bf_lo(o.y); a0[3] = a0[3] * (ub(g.x, 3) * q) + bf_hi(o.y);
;                         a1[0] = a1[0] * (ub(g.y, 0) * q) + bf_lo(o.z); a1[1] = a1[1] * (ub(g.y, 1) * q) + bf_hi(o.z); a1[2] = a1[2] * (ub(g.y, 2) * q) + bf_lo(o.w); a1[3] = a1[3] * (ub(g.y, 3) * q) + bf_hi(o.w);
;                         asm volatile("" : "+v"(a0), "+v"(a1)); }
;     ...
; #pragma unroll
;         for (int ai = 0; ai < 2; ++ai)
; #pragma unroll
;             for (int m = 0; m < 4; ++m)
; #pragma unroll
;                 for (int bj = 0; bj < 2; ++bj) { const f32x4 a0 = acc[ai][bj][m][0], a1 = acc[ai][bj][m][1];
;                     u32x4 w; w.x = cvt_pk_bf16(a0[0], a0[1]); w.y = cvt_pk_bf16(a0[2], a0[3]); w.z = cvt_pk_bf16(a1[0], a1[1]); w.w = cvt_pk_bf16(a1[2], a1[3]);
;                     *(u32x4*)mg_at(u, ai, m, bj, wr, wc, fr, fq) = w; }
	v_lshlrev_b32_e32 v134, 16, v148
	v_and_b32_e32 v135, 0xffff0000, v148
	v_pk_fma_f32 v[12:13], v[12:13], v[132:133], v[134:135]
	v_cvt_f32_ubyte3_e32 v133, v108
	v_cvt_f32_ubyte2_e32 v132, v108
	v_pk_mul_f32 v[132:133], v[132:133], s[10:11] op_sel_hi:[1,0]
	v_lshlrev_b32_e32 v134, 16, v149
	v_and_b32_e32 v135, 0xffff0000, v149
	v_pk_fma_f32 v[14:15], v[14:15], v[132:133], v[134:135]
	v_cvt_f32_ubyte1_e32 v133, v109
	v_cvt_f32_ubyte0_e32 v132, v109
	v_pk_mul_f32 v[132:133], v[132:133], s[10:11] op_sel_hi:[1,0]
	v_lshlrev_b32_e32 v134, 16, v150
	v_and_b32_e32 v135, 0xffff0000, v150
	v_pk_fma_f32 v[8:9], v[8:9], v[132:133], v[134:135]
	v_cvt_f32_ubyte3_e32 v133, v109
	v_cvt_f32_ubyte2_e32 v132, v109
	v_pk_mul_f32 v[108:109], v[132:133], s[10:11] op_sel_hi:[1,0]
	v_lshlrev_b32_e32 v132, 16, v151
	v_and_b32_e32 v133, 0xffff0000, v151
	v_pk_fma_f32 v[10:11], v[10:11], v[108:109], v[132:133]
	v_cvt_f32_ubyte1_e32 v109, v110
	v_cvt_f32_ubyte0_e32 v108, v110
	v_pk_mul_f32 v[108:109], v[108:109], s[10:11] op_sel_hi:[1,0]
	s_waitcnt vmcnt(0)
	v_lshlrev_b32_e32 v132, 16, v144
	v_and_b32_e32 v133, 0xffff0000, v144
	v_pk_fma_f32 v[4:5], v[4:5], v[108:109], v[132:133]
	v_cvt_f32_ubyte3_e32 v109, v110
	v_cvt_f32_ubyte2_e32 v108, v110
	v_pk_mul_f32 v[108:109], v[108:109], s[10:11] op_sel_hi:[1,0]
	v_lshlrev_b32_e32 v132, 16, v145
	v_and_b32_e32 v133, 0xffff0000, v145
	v_pk_fma_f32 v[6:7], v[6:7], v[108:109], v[132:133]
	v_cvt_f32_ubyte1_e32 v109, v111
	v_cvt_f32_ubyte0_e32 v108, v111
	v_pk_mul_f32 v[108:109], v[108:109], s[10:11] op_sel_hi:[1,0]
	v_lshlrev_b32_e32 v132, 16, v146
	v_and_b32_e32 v133, 0xffff0000, v146
	v_pk_fma_f32 v[0:1], v[0:1], v[108:109], v[132:133]
	v_cvt_f32_ubyte3_e32 v109, v111
	v_cvt_f32_ubyte2_e32 v108, v111
	v_pk_mul_f32 v[108:109], v[108:109], s[10:11] op_sel_hi:[1,0]
	v_lshlrev_b32_e32 v110, 16, v147
	v_and_b32_e32 v111, 0xffff0000, v147
	v_pk_fma_f32 v[2:3], v[2:3], v[108:109], v[110:111]
	s_nop 0
	v_cvt_pk_bf16_f32 v108, v128, v129
	v_cvt_pk_bf16_f32 v109, v130, v131
	v_cvt_pk_bf16_f32 v110, v124, v125
	v_lshl_add_u64 v[124:125], s[64:65], 0, v[176:177]
	v_cvt_pk_bf16_f32 v111, v126, v127
	global_store_dwordx4 v[124:125], v[108:111], off sc1
	s_nop 1
	v_cvt_pk_bf16_f32 v108, v120, v121
	v_cvt_pk_bf16_f32 v109, v122, v123
	v_cvt_pk_bf16_f32 v110, v116, v117
	v_lshl_add_u64 v[116:117], s[62:63], 0, v[176:177]
	v_cvt_pk_bf16_f32 v111, v118, v119
	global_store_dwordx4 v[116:117], v[108:111], off sc1
	s_nop 1
	v_cvt_pk_bf16_f32 v108, v112, v113
	v_cvt_pk_bf16_f32 v109, v114, v115
	v_cvt_pk_bf16_f32 v110, v104, v105
	v_lshl_add_u64 v[104:105], s[64:65], 0, v[178:179]
	v_cvt_pk_bf16_f32 v111, v106, v107
	global_store_dwordx4 v[104:105], v[108:111], off sc1
	v_cvt_pk_bf16_f32 v100, v100, v101
	v_cvt_pk_bf16_f32 v101, v102, v103
	v_cvt_pk_bf16_f32 v102, v96, v97
	v_lshl_add_u64 v[96:97], s[62:63], 0, v[178:179]
	v_cvt_pk_bf16_f32 v103, v98, v99
	global_store_dwordx4 v[96:97], v[100:103], off sc1
	v_cvt_pk_bf16_f32 v92, v92, v93
	v_cvt_pk_bf16_f32 v93, v94, v95
	v_cvt_pk_bf16_f32 v94, v88, v89
	v_lshl_add_u64 v[88:89], s[64:65], 0, v[180:181]
	v_cvt_pk_bf16_f32 v95, v90, v91
	global_store_dwordx4 v[88:89], v[92:95], off sc1
	v_cvt_pk_bf16_f32 v84, v84, v85
	v_cvt_pk_bf16_f32 v85, v86, v87
	v_cvt_pk_bf16_f32 v86, v80, v81
	v_lshl_add_u64 v[80:81], s[62:63], 0, v[180:181]
	v_cvt_pk_bf16_f32 v87, v82, v83
	global_store_dwordx4 v[80:81], v[84:87], off sc1
	v_cvt_pk_bf16_f32 v76, v76, v77
	v_cvt_pk_bf16_f32 v77, v78, v79
	v_cvt_pk_bf16_f32 v78, v72, v73
	v_lshl_add_u64 v[72:73], s[64:65], 0, v[182:183]
	v_cvt_pk_bf16_f32 v79, v74, v75
	global_store_dwordx4 v[72:73], v[76:79], off sc1
	v_cvt_pk_bf16_f32 v68, v68, v69
	v_cvt_pk_bf16_f32 v69, v70, v71
	v_cvt_pk_bf16_f32 v70, v64, v65
	v_lshl_add_u64 v[64:65], s[62:63], 0, v[182:183]
	s_add_u32 s62, s6, s68
	s_addc_u32 s63, s7, s69
	s_add_u32 s64, s6, s66
	v_cvt_pk_bf16_f32 v71, v66, v67
	global_store_dwordx4 v[64:65], v[68:71], off sc1
	v_cvt_pk_bf16_f32 v60, v60, v61
	v_cvt_pk_bf16_f32 v61, v62, v63
	v_cvt_pk_bf16_f32 v62, v56, v57
	v_lshl_add_u64 v[56:57], s[62:63], 0, v[176:177]
	s_addc_u32 s65, s7, s67
	v_cvt_pk_bf16_f32 v63, v58, v59
	global_store_dwordx4 v[56:57], v[60:63], off sc1
	v_cvt_pk_bf16_f32 v52, v52, v53
	v_cvt_pk_bf16_f32 v53, v54, v55
	v_cvt_pk_bf16_f32 v54, v48, v49
	v_lshl_add_u64 v[48:49], s[64:65], 0, v[176:177]
	v_cvt_pk_bf16_f32 v55, v50, v51
	global_store_dwordx4 v[48:49], v[52:55], off sc1
	v_cvt_pk_bf16_f32 v44, v44, v45
	v_cvt_pk_bf16_f32 v45, v46, v47
	v_cvt_pk_bf16_f32 v46, v40, v41
	v_lshl_add_u64 v[40:41], s[62:63], 0, v[178:179]
	v_cvt_pk_bf16_f32 v47, v42, v43
	global_store_dwordx4 v[40:41], v[44:47], off sc1
	v_cvt_pk_bf16_f32 v36, v36, v37
	v_cvt_pk_bf16_f32 v37, v38, v39
	v_cvt_pk_bf16_f32 v38, v32, v33
	v_lshl_add_u64 v[32:33], s[64:65], 0, v[178:179]
	v_cvt_pk_bf16_f32 v39, v34, v35
	global_store_dwordx4 v[32:33], v[36:39], off sc1
	v_cvt_pk_bf16_f32 v28, v28, v29
	v_cvt_pk_bf16_f32 v29, v30, v31
	v_cvt_pk_bf16_f32 v30, v24, v25
	v_lshl_add_u64 v[24:25], s[62:63], 0, v[180:181]
	v_cvt_pk_bf16_f32 v31, v26, v27
	global_store_dwordx4 v[24:25], v[28:31], off sc1
	v_cvt_pk_bf16_f32 v20, v20, v21
	v_cvt_pk_bf16_f32 v21, v22, v23
	v_cvt_pk_bf16_f32 v22, v16, v17
	v_lshl_add_u64 v[16:17], s[64:65], 0, v[180:181]
	v_cvt_pk_bf16_f32 v23, v18, v19
	global_store_dwordx4 v[16:17], v[20:23], off sc1
	v_cvt_pk_bf16_f32 v12, v12, v13
	v_cvt_pk_bf16_f32 v13, v14, v15
	v_cvt_pk_bf16_f32 v14, v8, v9
	v_lshl_add_u64 v[8:9], s[62:63], 0, v[182:183]
	v_cvt_pk_bf16_f32 v15, v10, v11
	global_store_dwordx4 v[8:9], v[12:15], off sc1
	v_cvt_pk_bf16_f32 v4, v4, v5
	v_cvt_pk_bf16_f32 v5, v6, v7
	v_cvt_pk_bf16_f32 v6, v0, v1
	v_lshl_add_u64 v[0:1], s[64:65], 0, v[182:183]
	s_andn2_b64 vcc, exec, s[2:3]
	s_mov_b64 s[2:3], -1
	v_cvt_pk_bf16_f32 v7, v2, v3
	global_store_dwordx4 v[0:1], v[4:7], off sc1
	s_cbranch_vccnz .LBB0_662
	s_andn2_b64 vcc, exec, s[48:49]
	s_cbranch_vccnz .LBB0_661
	s_barrier
	s_branch .LBB0_661

; __device__ __forceinline__ unsigned cvt_pk_bf16(float lo, float hi) { unsigned r; asm volatile("v_cvt_pk_bf16_f32 %0, %1, %2" : "=v"(r) : "v"(lo), "v"(hi)); return r; }
; __device__ __forceinline__ float bf_lo(unsigned w) { return __uint_as_float(w << 16); }
; __device__ __forceinline__ float bf_hi(unsigned w) { return __uint_as_float(w & 0xffff0000u); }
;     __device__ __forceinline__ void operator()(f32x4 (&acc)[2][2][4][2], const Unit& u, int wr, int wc, int fr, int fq) const {
;     ...
;             for (int m = 0; m < 4; ++m) { const int row = row0 + ai * HALF + m * 16; float s = 0.f;
; #pragma unroll
;                 for (int bj = 0; bj < 2; ++bj) { const size_t o2 = (size_t)row * 1024 + col0 + bj * HALF; const u32x4 p = pre[ai][m][bj]; const f32x4 a0 = acc[ai][bj][m][0], a1 = acc[ai][bj][m][1];
;                     f32x4 o0, o1; o0[0] = bf_lo(p.x) + a0[0] * alpha; o0[1] = bf_hi(p.x) + a0[1] * alpha; o0[2] = bf_lo(p.y) + a0[2] * alpha; o0[3] = bf_hi(p.y) + a0[3] * alpha;
;                     o1[0] = bf_lo(p.z) + a1[0] * alpha; o1[1] = bf_hi(p.z) + a1[1] * alpha; o1[2] = bf_lo(p.w) + a1[2] * alpha; o1[3] = bf_hi(p.w) + a1[3] * alpha;
;                     s += ((o0[0] * o0[0] + o0[1] * o0[1]) + (o0[2] * o0[2] + o0[3] * o0[3])) + ((o1[0] * o1[0] + o1[1] * o1[1]) + (o1[2] * o1[2] + o1[3] * o1[3]));
;                     u32x4 w; w.x = cvt_pk_bf16(o0[0], o0[1]); w.y = cvt_pk_bf16(o0[2], o0[3]); w.z = cvt_pk_bf16(o1[0], o1[1]); w.w = cvt_pk_bf16(o1[2], o1[3]);
;                     *(u32x4*)hb_at(u, ai, m, bj, wr, wc, fr, fq) = w;
;                     if (out) { *(f32x4*)(out + o2) = o0; *(f32x4*)(out + o2 + 4) = o1; } }
;                 s += __shfl_xor(s, 16); s += __shfl_xor(s, 32);
;                 if (ssq && fq == 0) atomicAdd(ssq + row, s); }
.Lnoal_5:
	s_waitcnt vmcnt(15)
	v_lshlrev_b32_e32 v209, 16, v220
	v_and_b32_e32 v217, 0xffff0000, v220
	v_lshlrev_b32_e32 v219, 16, v221
	v_and_b32_e32 v220, 0xffff0000, v221
	v_lshlrev_b32_e32 v221, 16, v222
	v_and_b32_e32 v222, 0xffff0000, v222
	v_lshlrev_b32_e32 v230, 16, v223
	v_and_b32_e32 v223, 0xffff0000, v223
	v_add_f32_e32 v125, v125, v217
	v_add_f32_e32 v127, v127, v220
	v_add_f32_e32 v217, v121, v222
	v_add_f32_e32 v123, v123, v223
	v_add_f32_e32 v124, v124, v209
	v_add_f32_e32 v126, v126, v219
	v_add_f32_e32 v209, v120, v221
	v_add_f32_e32 v219, v122, v230
	s_waitcnt vmcnt(14)
	v_lshlrev_b32_e32 v222, 16, v225
	v_and_b32_e32 v223, 0xffff0000, v225
	v_mul_f32_e32 v225, v125, v125
	v_mul_f32_e32 v230, v127, v127
	v_mul_f32_e32 v231, v217, v217
	v_mul_f32_e32 v232, v123, v123
	v_cvt_pk_bf16_f32 v120, v124, v125
	v_cvt_pk_bf16_f32 v121, v126, v127
	v_fmac_f32_e32 v225, v124, v124
	v_fmac_f32_e32 v230, v126, v126
	v_fmac_f32_e32 v231, v209, v209
	v_fmac_f32_e32 v232, v219, v219
	v_lshlrev_b32_e32 v220, 16, v224
	v_and_b32_e32 v221, 0xffff0000, v224
	v_lshlrev_b32_e32 v224, 16, v226
	v_cvt_pk_bf16_f32 v122, v209, v217
	v_cvt_pk_bf16_f32 v123, v219, v123
	global_store_dwordx4 v[228:229], v[120:123], off sc1
	v_add_f32_e32 v117, v117, v221
	v_add_f32_e32 v119, v119, v223
	v_add_f32_e32 v120, v225, v230
	v_add_f32_e32 v121, v231, v232
	v_add_f32_e32 v120, v120, v121
	v_add_f32_e32 v121, v112, v224
	v_and_b32_e32 v112, 0xffff0000, v226
	v_add_f32_e32 v113, v113, v112
	v_lshlrev_b32_e32 v112, 16, v227
	v_add_f32_e32 v114, v114, v112
	v_and_b32_e32 v112, 0xffff0000, v227
	v_add_f32_e32 v116, v116, v220
	v_add_f32_e32 v118, v118, v222
	v_add_f32_e32 v115, v115, v112
	v_mul_f32_e32 v112, v117, v117
	v_mul_f32_e32 v122, v119, v119
	v_fmac_f32_e32 v112, v116, v116
	v_fmac_f32_e32 v122, v118, v118
	v_add_f32_e32 v112, v112, v122
	v_mul_f32_e32 v122, v113, v113
	v_mul_f32_e32 v123, v115, v115
	v_fmac_f32_e32 v122, v121, v121
	v_fmac_f32_e32 v123, v114, v114
	v_add_f32_e32 v122, v122, v123
	v_add_f32_e32 v112, v112, v122
	v_cvt_pk_bf16_f32 v116, v116, v117
	v_and_b32_e32 v117, 64, v216
	v_add_f32_e32 v120, v120, v112
	v_xor_b32_e32 v112, 16, v216
	v_add_u32_e32 v122, 64, v117
	v_cmp_lt_i32_e32 vcc, v112, v122
	v_cvt_pk_bf16_f32 v117, v118, v119
	v_cvt_pk_bf16_f32 v118, v121, v113
	v_xor_b32_e32 v113, 32, v216
	v_cvt_pk_bf16_f32 v119, v114, v115
	v_ashrrev_i32_e32 v209, 31, v208
	v_cndmask_b32_e32 v112, v216, v112, vcc
	v_lshlrev_b32_e32 v112, 2, v112
	ds_bpermute_b32 v123, v112, v120
	v_cmp_lt_i32_e32 vcc, v113, v122
	s_waitcnt lgkmcnt(0)
	v_add_f32_e32 v114, v120, v123
	v_cndmask_b32_e32 v113, v216, v113, vcc
	v_lshlrev_b32_e32 v113, 2, v113
	ds_bpermute_b32 v115, v113, v114
	v_lshl_add_u64 v[120:121], s[70:71], 0, v[186:187]
	global_store_dwordx4 v[120:121], v[116:119], off sc1
	s_and_saveexec_b64 s[72:73], s[2:3]
	s_cbranch_execz .LBB0_756
	v_lshl_add_u64 v[116:117], v[208:209], 2, s[0:1]
	s_waitcnt lgkmcnt(0)
	v_add_f32_e32 v114, v114, v115
	global_atomic_add_f32 v[116:117], v114, off
.LBB0_756:
	s_or_b64 exec, exec, s[72:73]
	s_waitcnt vmcnt(15)
	v_lshlrev_b32_e32 v114, 16, v180
	v_add_f32_e32 v108, v108, v114
	v_and_b32_e32 v114, 0xffff0000, v180
	v_add_f32_e32 v109, v109, v114
	v_lshlrev_b32_e32 v114, 16, v181
	v_add_f32_e32 v110, v110, v114
	v_and_b32_e32 v114, 0xffff0000, v181
	v_add_f32_e32 v111, v111, v114
	v_lshlrev_b32_e32 v114, 16, v182
	v_add_f32_e32 v114, v104, v114
	v_and_b32_e32 v104, 0xffff0000, v182
	s_waitcnt lgkmcnt(0)
	v_add_f32_e32 v115, v105, v104
	v_lshlrev_b32_e32 v104, 16, v183
	v_add_f32_e32 v116, v106, v104
	v_and_b32_e32 v104, 0xffff0000, v183
	v_add_f32_e32 v107, v107, v104
	v_mul_f32_e32 v104, v109, v109
	v_mul_f32_e32 v105, v111, v111
	v_fmac_f32_e32 v104, v108, v108
	v_fmac_f32_e32 v105, v110, v110
	v_add_f32_e32 v104, v104, v105
	v_mul_f32_e32 v105, v115, v115
	v_mul_f32_e32 v106, v107, v107
	v_fmac_f32_e32 v105, v114, v114
	v_fmac_f32_e32 v106, v116, v116
	v_add_f32_e32 v105, v105, v106
	v_add_f32_e32 v117, v104, v105
	v_cvt_pk_bf16_f32 v104, v108, v109
	s_waitcnt vmcnt(14)
	v_lshlrev_b32_e32 v108, 16, v176
	v_add_f32_e32 v100, v100, v108
	v_and_b32_e32 v108, 0xffff0000, v176
	v_add_f32_e32 v101, v101, v108
	v_lshlrev_b32_e32 v108, 16, v177
	v_add_f32_e32 v102, v102, v108
	v_and_b32_e32 v108, 0xffff0000, v177
	v_add_f32_e32 v103, v103, v108
	v_lshlrev_b32_e32 v108, 16, v178
	v_add_f32_e32 v108, v96, v108
	v_and_b32_e32 v96, 0xffff0000, v178
	v_add_f32_e32 v109, v97, v96
	v_lshlrev_b32_e32 v96, 16, v179
	v_cvt_pk_bf16_f32 v105, v110, v111
	v_add_f32_e32 v110, v98, v96
	v_and_b32_e32 v96, 0xffff0000, v179
	v_add_f32_e32 v111, v99, v96
	v_mul_f32_e32 v96, v101, v101
	v_mul_f32_e32 v97, v103, v103
	v_fmac_f32_e32 v96, v100, v100
	v_fmac_f32_e32 v97, v102, v102
	v_add_f32_e32 v96, v96, v97
	v_mul_f32_e32 v97, v109, v109
	v_mul_f32_e32 v98, v111, v111
	v_fmac_f32_e32 v97, v108, v108
	v_fmac_f32_e32 v98, v110, v110
	v_add_f32_e32 v97, v97, v98
	v_add_f32_e32 v96, v96, v97
	v_cvt_pk_bf16_f32 v106, v114, v115
	v_add_f32_e32 v114, v117, v96
	ds_bpermute_b32 v115, v112, v114
	v_lshl_add_u64 v[96:97], s[68:69], 0, v[192:193]
	v_cvt_pk_bf16_f32 v107, v116, v107
	global_store_dwordx4 v[96:97], v[104:107], off sc1
	v_cvt_pk_bf16_f32 v98, v100, v101
	s_waitcnt lgkmcnt(0)
	v_add_f32_e32 v96, v114, v115
	ds_bpermute_b32 v97, v113, v96
	v_cvt_pk_bf16_f32 v99, v102, v103
	v_lshl_add_u64 v[102:103], s[70:71], 0, v[192:193]
	v_cvt_pk_bf16_f32 v100, v108, v109
	v_cvt_pk_bf16_f32 v101, v110, v111
	global_store_dwordx4 v[102:103], v[98:101], off sc1
	s_and_saveexec_b64 s[72:73], s[2:3]
	s_cbranch_execz .LBB0_758
	v_lshl_add_u64 v[98:99], v[208:209], 2, s[0:1]
	s_waitcnt lgkmcnt(0)
	v_add_f32_e32 v96, v96, v97
	global_atomic_add_f32 v[98:99], v96, off offset:64
; __device__ __forceinline__ unsigned cvt_pk_bf16(float lo, float hi) { unsigned r; asm volatile("v_cvt_pk_bf16_f32 %0, %1, %2" : "=v"(r) : "v"(lo), "v"(hi)); return r; }
; __device__ __forceinline__ float bf_lo(unsigned w) { return __uint_as_float(w << 16); }
; __device__ __forceinline__ float bf_hi(unsigned w) { return __uint_as_float(w & 0xffff0000u); }
;     __device__ __forceinline__ void operator()(f32x4 (&acc)[2][2][4][2], const Unit& u, int wr, int wc, int fr, int fq) const {
;     ...
;             for (int m = 0; m < 4; ++m) { const int row = row0 + ai * HALF + m * 16; float s = 0.f;
; #pragma unroll
;                 for (int bj = 0; bj < 2; ++bj) { const size_t o2 = (size_t)row * 1024 + col0 + bj * HALF; const u32x4 p = pre[ai][m][bj]; const f32x4 a0 = acc[ai][bj][m][0], a1 = acc[ai][bj][m][1];
;                     f32x4 o0, o1; o0[0] = bf_lo(p.x) + a0[0] * alpha; o0[1] = bf_hi(p.x) + a0[1] * alpha; o0[2] = bf_lo(p.y) + a0[2] * alpha; o0[3] = bf_hi(p.y) + a0[3] * alpha;
;                     o1[0] = bf_lo(p.z) + a1[0] * alpha; o1[1] = bf_hi(p.z) + a1[1] * alpha; o1[2] = bf_lo(p.w) + a1[2] * alpha; o1[3] = bf_hi(p.w) + a1[3] * alpha;
;                     s += ((o0[0] * o0[0] + o0[1] * o0[1]) + (o0[2] * o0[2] + o0[3] * o0[3])) + ((o1[0] * o1[0] + o1[1] * o1[1]) + (o1[2] * o1[2] + o1[3] * o1[3]));
;                     u32x4 w; w.x = cvt_pk_bf16(o0[0], o0[1]); w.y = cvt_pk_bf16(o0[2], o0[3]); w.z = cvt_pk_bf16(o1[0], o1[1]); w.w = cvt_pk_bf16(o1[2], o1[3]);
;                     *(u32x4*)hb_at(u, ai, m, bj, wr, wc, fr, fq) = w;
;                     if (out) { *(f32x4*)(out + o2) = o0; *(f32x4*)(out + o2 + 4) = o1; } }
;                 s += __shfl_xor(s, 16); s += __shfl_xor(s, 32);
;                 if (ssq && fq == 0) atomicAdd(ssq + row, s); }
.LBB0_758:
	s_or_b64 exec, exec, s[72:73]
	s_waitcnt vmcnt(15)
	v_lshlrev_b32_e32 v96, 16, v172
	v_add_f32_e32 v92, v92, v96
	v_and_b32_e32 v96, 0xffff0000, v172
	v_add_f32_e32 v93, v93, v96
	v_lshlrev_b32_e32 v96, 16, v173
	v_add_f32_e32 v94, v94, v96
	v_and_b32_e32 v96, 0xffff0000, v173
	v_add_f32_e32 v95, v95, v96
	v_lshlrev_b32_e32 v96, 16, v174
	v_add_f32_e32 v96, v88, v96
	v_and_b32_e32 v88, 0xffff0000, v174
	s_waitcnt lgkmcnt(0)
	v_add_f32_e32 v97, v89, v88
	v_lshlrev_b32_e32 v88, 16, v175
	v_add_f32_e32 v98, v90, v88
	v_and_b32_e32 v88, 0xffff0000, v175
	v_add_f32_e32 v91, v91, v88
	v_mul_f32_e32 v88, v93, v93
	v_mul_f32_e32 v89, v95, v95
	v_fmac_f32_e32 v88, v92, v92
	v_fmac_f32_e32 v89, v94, v94
	v_add_f32_e32 v88, v88, v89
	v_mul_f32_e32 v89, v97, v97
	v_mul_f32_e32 v90, v91, v91
	v_fmac_f32_e32 v89, v96, v96
	v_fmac_f32_e32 v90, v98, v98
	v_add_f32_e32 v89, v89, v90
	v_add_f32_e32 v99, v88, v89
	v_cvt_pk_bf16_f32 v88, v92, v93
	s_waitcnt vmcnt(14)
	v_lshlrev_b32_e32 v92, 16, v168
	v_add_f32_e32 v84, v84, v92
	v_and_b32_e32 v92, 0xffff0000, v168
	v_add_f32_e32 v85, v85, v92
	v_lshlrev_b32_e32 v92, 16, v169
	v_add_f32_e32 v86, v86, v92
	v_and_b32_e32 v92, 0xffff0000, v169
	v_add_f32_e32 v87, v87, v92
	v_lshlrev_b32_e32 v92, 16, v170
	v_add_f32_e32 v92, v80, v92
	v_and_b32_e32 v80, 0xffff0000, v170
	v_add_f32_e32 v93, v81, v80
	v_lshlrev_b32_e32 v80, 16, v171
	v_cvt_pk_bf16_f32 v89, v94, v95
	v_add_f32_e32 v94, v82, v80
	v_and_b32_e32 v80, 0xffff0000, v171
	v_add_f32_e32 v95, v83, v80
	v_mul_f32_e32 v80, v85, v85
	v_mul_f32_e32 v81, v87, v87
	v_fmac_f32_e32 v80, v84, v84
	v_fmac_f32_e32 v81, v86, v86
	v_add_f32_e32 v80, v80, v81
	v_mul_f32_e32 v81, v93, v93
	v_mul_f32_e32 v82, v95, v95
	v_fmac_f32_e32 v81, v92, v92
	v_fmac_f32_e32 v82, v94, v94
	v_add_f32_e32 v81, v81, v82
	v_add_f32_e32 v80, v80, v81
	v_cvt_pk_bf16_f32 v90, v96, v97
	v_add_f32_e32 v96, v99, v80
	ds_bpermute_b32 v97, v112, v96
	v_lshl_add_u64 v[80:81], s[68:69], 0, v[194:195]
	v_cvt_pk_bf16_f32 v91, v98, v91
	global_store_dwordx4 v[80:81], v[88:91], off sc1
	v_cvt_pk_bf16_f32 v82, v84, v85
	s_waitcnt lgkmcnt(0)
	v_add_f32_e32 v80, v96, v97
	ds_bpermute_b32 v81, v113, v80
	v_cvt_pk_bf16_f32 v83, v86, v87
	v_lshl_add_u64 v[86:87], s[70:71], 0, v[194:195]
	v_cvt_pk_bf16_f32 v84, v92, v93
	v_cvt_pk_bf16_f32 v85, v94, v95
	global_store_dwordx4 v[86:87], v[82:85], off sc1
	s_and_saveexec_b64 s[72:73], s[2:3]
	s_cbranch_execz .LBB0_760
	v_lshl_add_u64 v[82:83], v[208:209], 2, s[0:1]
	s_waitcnt lgkmcnt(0)
	v_add_f32_e32 v80, v80, v81
	global_atomic_add_f32 v[82:83], v80, off offset:128
.LBB0_760:
	s_or_b64 exec, exec, s[72:73]
	s_waitcnt vmcnt(15)
	v_lshlrev_b32_e32 v80, 16, v164
	v_add_f32_e32 v76, v76, v80
	v_and_b32_e32 v80, 0xffff0000, v164
	v_add_f32_e32 v77, v77, v80
	v_lshlrev_b32_e32 v80, 16, v165
	v_add_f32_e32 v78, v78, v80
	v_and_b32_e32 v80, 0xffff0000, v165
	v_add_f32_e32 v79, v79, v80
	v_lshlrev_b32_e32 v80, 16, v166
	v_add_f32_e32 v80, v72, v80
	v_and_b32_e32 v72, 0xffff0000, v166
	s_waitcnt lgkmcnt(0)
	v_add_f32_e32 v81, v73, v72
	v_lshlrev_b32_e32 v72, 16, v167
	v_add_f32_e32 v82, v74, v72
	v_and_b32_e32 v72, 0xffff0000, v167
	v_add_f32_e32 v75, v75, v72
	v_mul_f32_e32 v72, v77, v77
	v_mul_f32_e32 v73, v79, v79
	v_fmac_f32_e32 v72, v76, v76
	v_fmac_f32_e32 v73, v78, v78
	v_add_f32_e32 v72, v72, v73
	v_mul_f32_e32 v73, v81, v81
	v_mul_f32_e32 v74, v75, v75
	v_fmac_f32_e32 v73, v80, v80
	v_fmac_f32_e32 v74, v82, v82
	v_add_f32_e32 v73, v73, v74
	v_add_f32_e32 v83, v72, v73
	v_cvt_pk_bf16_f32 v72, v76, v77
	s_waitcnt vmcnt(14)
	v_lshlrev_b32_e32 v76, 16, v160
	v_add_f32_e32 v68, v68, v76
	v_and_b32_e32 v76, 0xffff0000, v160
	v_add_f32_e32 v69, v69, v76
	v_lshlrev_b32_e32 v76, 16, v161
	v_add_f32_e32 v70, v70, v76
	v_and_b32_e32 v76, 0xffff0000, v161
	v_add_f32_e32 v71, v71, v76
	v_lshlrev_b32_e32 v76, 16, v162
	v_add_f32_e32 v76, v64, v76
	v_and_b32_e32 v64, 0xffff0000, v162
	v_add_f32_e32 v77, v65, v64
	v_lshlrev_b32_e32 v64, 16, v163
	v_cvt_pk_bf16_f32 v73, v78, v79
	v_add_f32_e32 v78, v66, v64
	v_and_b32_e32 v64, 0xffff0000, v163
	v_add_f32_e32 v79, v67, v64
	v_mul_f32_e32 v64, v69, v69
	v_mul_f32_e32 v65, v71, v71
	v_fmac_f32_e32 v64, v68, v68
	v_fmac_f32_e32 v65, v70, v70
	v_add_f32_e32 v64, v64, v65
	v_mul_f32_e32 v65, v77, v77
	v_mul_f32_e32 v66, v79, v79
	v_fmac_f32_e32 v65, v76, v76
	v_fmac_f32_e32 v66, v78, v78
	v_add_f32_e32 v65, v65, v66
	v_add_f32_e32 v64, v64, v65
	v_cvt_pk_bf16_f32 v74, v80, v81
	v_add_f32_e32 v80, v83, v64
	ds_bpermute_b32 v81, v112, v80
	v_lshl_add_u64 v[64:65], s[68:69], 0, v[184:185]
	v_cvt_pk_bf16_f32 v75, v82, v75
	global_store_dwordx4 v[64:65], v[72:75], off sc1
	v_cvt_pk_bf16_f32 v66, v68, v69
	s_waitcnt lgkmcnt(0)
	v_add_f32_e32 v64, v80, v81
	ds_bpermute_b32 v65, v113, v64
	v_cvt_pk_bf16_f32 v67, v70, v71
	v_lshl_add_u64 v[70:71], s[70:71], 0, v[184:185]
	v_cvt_pk_bf16_f32 v68, v76, v77
	v_cvt_pk_bf16_f32 v69, v78, v79
	global_store_dwordx4 v[70:71], v[66:69], off sc1
	s_and_saveexec_b64 s[68:69], s[2:3]
	s_cbranch_execz .LBB0_762
	v_lshl_add_u64 v[66:67], v[208:209], 2, s[0:1]
	s_waitcnt lgkmcnt(0)
	v_add_f32_e32 v64, v64, v65
	global_atomic_add_f32 v[66:67], v64, off offset:192
; __device__ __forceinline__ unsigned cvt_pk_bf16(float lo, float hi) { unsigned r; asm volatile("v_cvt_pk_bf16_f32 %0, %1, %2" : "=v"(r) : "v"(lo), "v"(hi)); return r; }
; __device__ __forceinline__ float bf_lo(unsigned w) { return __uint_as_float(w << 16); }
; __device__ __forceinline__ float bf_hi(unsigned w) { return __uint_as_float(w & 0xffff0000u); }
;     __device__ __forceinline__ void operator()(f32x4 (&acc)[2][2][4][2], const Unit& u, int wr, int wc, int fr, int fq) const {
;     ...
;             for (int m = 0; m < 4; ++m) { const int row = row0 + ai * HALF + m * 16; float s = 0.f;
; #pragma unroll
;                 for (int bj = 0; bj < 2; ++bj) { const size_t o2 = (size_t)row * 1024 + col0 + bj * HALF; const u32x4 p = pre[ai][m][bj]; const f32x4 a0 = acc[ai][bj][m][0], a1 = acc[ai][bj][m][1];
;                     f32x4 o0, o1; o0[0] = bf_lo(p.x) + a0[0] * alpha; o0[1] = bf_hi(p.x) + a0[1] * alpha; o0[2] = bf_lo(p.y) + a0[2] * alpha; o0[3] = bf_hi(p.y) + a0[3] * alpha;
;                     o1[0] = bf_lo(p.z) + a1[0] * alpha; o1[1] = bf_hi(p.z) + a1[1] * alpha; o1[2] = bf_lo(p.w) + a1[2] * alpha; o1[3] = bf_hi(p.w) + a1[3] * alpha;
;                     s += ((o0[0] * o0[0] + o0[1] * o0[1]) + (o0[2] * o0[2] + o0[3] * o0[3])) + ((o1[0] * o1[0] + o1[1] * o1[1]) + (o1[2] * o1[2] + o1[3] * o1[3]));
;                     u32x4 w; w.x = cvt_pk_bf16(o0[0], o0[1]); w.y = cvt_pk_bf16(o0[2], o0[3]); w.z = cvt_pk_bf16(o1[0], o1[1]); w.w = cvt_pk_bf16(o1[2], o1[3]);
;                     *(u32x4*)hb_at(u, ai, m, bj, wr, wc, fr, fq) = w;
;                     if (out) { *(f32x4*)(out + o2) = o0; *(f32x4*)(out + o2 + 4) = o1; } }
;                 s += __shfl_xor(s, 16); s += __shfl_xor(s, 32);
;                 if (ssq && fq == 0) atomicAdd(ssq + row, s); }
.LBB0_762:
	s_or_b64 exec, exec, s[68:69]
	s_waitcnt vmcnt(15)
	v_lshlrev_b32_e32 v64, 16, v156
	v_add_f32_e32 v60, v60, v64
	v_and_b32_e32 v64, 0xffff0000, v156
	v_add_f32_e32 v61, v61, v64
	v_lshlrev_b32_e32 v64, 16, v157
	v_add_f32_e32 v62, v62, v64
	v_and_b32_e32 v64, 0xffff0000, v157
	v_add_f32_e32 v63, v63, v64
	v_lshlrev_b32_e32 v64, 16, v158
	v_add_f32_e32 v64, v56, v64
	v_and_b32_e32 v56, 0xffff0000, v158
	s_waitcnt lgkmcnt(0)
	v_add_f32_e32 v65, v57, v56
	v_lshlrev_b32_e32 v56, 16, v159
	v_add_f32_e32 v66, v58, v56
	v_and_b32_e32 v56, 0xffff0000, v159
	v_add_f32_e32 v59, v59, v56
	v_mul_f32_e32 v56, v61, v61
	v_mul_f32_e32 v57, v63, v63
	v_fmac_f32_e32 v56, v60, v60
	v_fmac_f32_e32 v57, v62, v62
	v_add_f32_e32 v56, v56, v57
	v_mul_f32_e32 v57, v65, v65
	v_mul_f32_e32 v58, v59, v59
	v_fmac_f32_e32 v57, v64, v64
	v_fmac_f32_e32 v58, v66, v66
	s_add_u32 s66, s12, s66
	v_add_f32_e32 v57, v57, v58
	s_addc_u32 s67, s13, s67
	v_add_f32_e32 v67, v56, v57
	v_cvt_pk_bf16_f32 v56, v60, v61
	v_lshl_add_u64 v[60:61], s[66:67], 0, v[186:187]
	v_cvt_pk_bf16_f32 v57, v62, v63
	v_cvt_pk_bf16_f32 v58, v64, v65
	v_cvt_pk_bf16_f32 v59, v66, v59
	global_store_dwordx4 v[60:61], v[56:59], off sc1
	s_add_u32 s64, s12, s64
	s_addc_u32 s65, s13, s65
	s_waitcnt vmcnt(15)
	v_lshlrev_b32_e32 v56, 16, v152
	v_add_f32_e32 v52, v52, v56
	v_and_b32_e32 v56, 0xffff0000, v152
	v_add_f32_e32 v53, v53, v56
	v_lshlrev_b32_e32 v56, 16, v153
	v_add_f32_e32 v54, v54, v56
	v_and_b32_e32 v56, 0xffff0000, v153
	v_add_f32_e32 v55, v55, v56
	v_lshlrev_b32_e32 v56, 16, v154
	v_add_f32_e32 v48, v48, v56
	v_and_b32_e32 v56, 0xffff0000, v154
	v_add_f32_e32 v49, v49, v56
	v_lshlrev_b32_e32 v56, 16, v155
	v_add_f32_e32 v56, v50, v56
	v_and_b32_e32 v50, 0xffff0000, v155
	v_add_f32_e32 v57, v51, v50
	v_mul_f32_e32 v50, v53, v53
	v_mul_f32_e32 v51, v55, v55
	v_fmac_f32_e32 v50, v52, v52
	v_fmac_f32_e32 v51, v54, v54
	v_add_f32_e32 v50, v50, v51
	v_mul_f32_e32 v51, v49, v49
	v_mul_f32_e32 v58, v57, v57
	v_fmac_f32_e32 v51, v48, v48
	v_fmac_f32_e32 v58, v56, v56
	v_add_f32_e32 v51, v51, v58
	v_add_f32_e32 v50, v50, v51
	v_add_f32_e32 v58, v67, v50
	ds_bpermute_b32 v59, v112, v58
	v_cvt_pk_bf16_f32 v50, v52, v53
	v_cvt_pk_bf16_f32 v51, v54, v55
	v_cvt_pk_bf16_f32 v52, v48, v49
	v_lshl_add_u64 v[54:55], s[64:65], 0, v[186:187]
	s_waitcnt lgkmcnt(0)
	v_add_f32_e32 v48, v58, v59
	ds_bpermute_b32 v49, v113, v48
	v_cvt_pk_bf16_f32 v53, v56, v57
	global_store_dwordx4 v[54:55], v[50:53], off sc1
	s_and_saveexec_b64 s[68:69], s[2:3]
	s_cbranch_execz .LBB0_764
	v_lshl_add_u64 v[50:51], v[208:209], 2, s[0:1]
	s_waitcnt lgkmcnt(0)
	v_add_f32_e32 v48, v48, v49
	global_atomic_add_f32 v[50:51], v48, off offset:512
.LBB0_764:
	s_or_b64 exec, exec, s[68:69]
	s_waitcnt vmcnt(15)
	v_lshlrev_b32_e32 v48, 16, v148
	v_add_f32_e32 v44, v44, v48
	v_and_b32_e32 v48, 0xffff0000, v148
	v_add_f32_e32 v45, v45, v48
	v_lshlrev_b32_e32 v48, 16, v149
	v_add_f32_e32 v46, v46, v48
	v_and_b32_e32 v48, 0xffff0000, v149
	v_add_f32_e32 v47, v47, v48
	v_lshlrev_b32_e32 v48, 16, v150
	v_add_f32_e32 v48, v40, v48
	v_and_b32_e32 v40, 0xffff0000, v150
	s_waitcnt lgkmcnt(0)
	v_add_f32_e32 v49, v41, v40
	v_lshlrev_b32_e32 v40, 16, v151
	v_add_f32_e32 v50, v42, v40
	v_and_b32_e32 v40, 0xffff0000, v151
	v_add_f32_e32 v43, v43, v40
	v_mul_f32_e32 v40, v45, v45
	v_mul_f32_e32 v41, v47, v47
	v_fmac_f32_e32 v40, v44, v44
	v_fmac_f32_e32 v41, v46, v46
	v_add_f32_e32 v40, v40, v41
	v_mul_f32_e32 v41, v49, v49
	v_mul_f32_e32 v42, v43, v43
	v_fmac_f32_e32 v41, v48, v48
	v_fmac_f32_e32 v42, v50, v50
	v_add_f32_e32 v41, v41, v42
	v_add_f32_e32 v51, v40, v41
	v_cvt_pk_bf16_f32 v40, v44, v45
	s_waitcnt vmcnt(14)
	v_lshlrev_b32_e32 v44, 16, v144
	v_add_f32_e32 v36, v36, v44
	v_and_b32_e32 v44, 0xffff0000, v144
	v_add_f32_e32 v37, v37, v44
	v_lshlrev_b32_e32 v44, 16, v145
	v_add_f32_e32 v38, v38, v44
	v_and_b32_e32 v44, 0xffff0000, v145
	v_add_f32_e32 v39, v39, v44
	v_lshlrev_b32_e32 v44, 16, v146
	v_add_f32_e32 v44, v32, v44
	v_and_b32_e32 v32, 0xffff0000, v146
	v_add_f32_e32 v45, v33, v32
	v_lshlrev_b32_e32 v32, 16, v147
	v_cvt_pk_bf16_f32 v41, v46, v47
	v_add_f32_e32 v46, v34, v32
	v_and_b32_e32 v32, 0xffff0000, v147
	v_add_f32_e32 v47, v35, v32
	v_mul_f32_e32 v32, v37, v37
	v_mul_f32_e32 v33, v39, v39
	v_fmac_f32_e32 v32, v36, v36
	v_fmac_f32_e32 v33, v38, v38
	v_add_f32_e32 v32, v32, v33
	v_mul_f32_e32 v33, v45, v45
	v_mul_f32_e32 v34, v47, v47
	v_fmac_f32_e32 v33, v44, v44
	v_fmac_f32_e32 v34, v46, v46
	v_add_f32_e32 v33, v33, v34
	v_add_f32_e32 v32, v32, v33
	v_cvt_pk_bf16_f32 v42, v48, v49
	v_add_f32_e32 v48, v51, v32
	ds_bpermute_b32 v49, v112, v48
	v_lshl_add_u64 v[32:33], s[66:67], 0, v[192:193]
	v_cvt_pk_bf16_f32 v43, v50, v43
	global_store_dwordx4 v[32:33], v[40:43], off sc1
	v_cvt_pk_bf16_f32 v34, v36, v37
	s_waitcnt lgkmcnt(0)
	v_add_f32_e32 v32, v48, v49
	ds_bpermute_b32 v33, v113, v32
	v_cvt_pk_bf16_f32 v35, v38, v39
	v_lshl_add_u64 v[38:39], s[64:65], 0, v[192:193]
	v_cvt_pk_bf16_f32 v36, v44, v45
	v_cvt_pk_bf16_f32 v37, v46, v47
	global_store_dwordx4 v[38:39], v[34:37], off sc1
	s_and_saveexec_b64 s[68:69], s[2:3]
	s_cbranch_execz .LBB0_766
	v_lshl_add_u64 v[34:35], v[208:209], 2, s[0:1]
	s_waitcnt lgkmcnt(0)
	v_add_f32_e32 v32, v32, v33
	global_atomic_add_f32 v[34:35], v32, off offset:576
; __device__ __forceinline__ unsigned cvt_pk_bf16(float lo, float hi) { unsigned r; asm volatile("v_cvt_pk_bf16_f32 %0, %1, %2" : "=v"(r) : "v"(lo), "v"(hi)); return r; }
; __device__ __forceinline__ float bf_lo(unsigned w) { return __uint_as_float(w << 16); }
; __device__ __forceinline__ float bf_hi(unsigned w) { return __uint_as_float(w & 0xffff0000u); }
;     __device__ __forceinline__ void operator()(f32x4 (&acc)[2][2][4][2], const Unit& u, int wr, int wc, int fr, int fq) const {
;     ...
;             for (int m = 0; m < 4; ++m) { const int row = row0 + ai * HALF + m * 16; float s = 0.f;
; #pragma unroll
;                 for (int bj = 0; bj < 2; ++bj) { const size_t o2 = (size_t)row * 1024 + col0 + bj * HALF; const u32x4 p = pre[ai][m][bj]; const f32x4 a0 = acc[ai][bj][m][0], a1 = acc[ai][bj][m][1];
;                     f32x4 o0, o1; o0[0] = bf_lo(p.x) + a0[0] * alpha; o0[1] = bf_hi(p.x) + a0[1] * alpha; o0[2] = bf_lo(p.y) + a0[2] * alpha; o0[3] = bf_hi(p.y) + a0[3] * alpha;
;                     o1[0] = bf_lo(p.z) + a1[0] * alpha; o1[1] = bf_hi(p.z) + a1[1] * alpha; o1[2] = bf_lo(p.w) + a1[2] * alpha; o1[3] = bf_hi(p.w) + a1[3] * alpha;
;                     s += ((o0[0] * o0[0] + o0[1] * o0[1]) + (o0[2] * o0[2] + o0[3] * o0[3])) + ((o1[0] * o1[0] + o1[1] * o1[1]) + (o1[2] * o1[2] + o1[3] * o1[3]));
;                     u32x4 w; w.x = cvt_pk_bf16(o0[0], o0[1]); w.y = cvt_pk_bf16(o0[2], o0[3]); w.z = cvt_pk_bf16(o1[0], o1[1]); w.w = cvt_pk_bf16(o1[2], o1[3]);
;                     *(u32x4*)hb_at(u, ai, m, bj, wr, wc, fr, fq) = w;
;                     if (out) { *(f32x4*)(out + o2) = o0; *(f32x4*)(out + o2 + 4) = o1; } }
;                 s += __shfl_xor(s, 16); s += __shfl_xor(s, 32);
;                 if (ssq && fq == 0) atomicAdd(ssq + row, s); }
.LBB0_766:
	s_or_b64 exec, exec, s[68:69]
	s_waitcnt vmcnt(15)
	v_lshlrev_b32_e32 v32, 16, v140
	v_add_f32_e32 v28, v28, v32
	v_and_b32_e32 v32, 0xffff0000, v140
	v_add_f32_e32 v29, v29, v32
	v_lshlrev_b32_e32 v32, 16, v141
	v_add_f32_e32 v30, v30, v32
	v_and_b32_e32 v32, 0xffff0000, v141
	v_add_f32_e32 v31, v31, v32
	v_lshlrev_b32_e32 v32, 16, v142
	v_add_f32_e32 v32, v24, v32
	v_and_b32_e32 v24, 0xffff0000, v142
	s_waitcnt lgkmcnt(0)
	v_add_f32_e32 v33, v25, v24
	v_lshlrev_b32_e32 v24, 16, v143
	v_add_f32_e32 v34, v26, v24
	v_and_b32_e32 v24, 0xffff0000, v143
	v_add_f32_e32 v27, v27, v24
	v_mul_f32_e32 v24, v29, v29
	v_mul_f32_e32 v25, v31, v31
	v_fmac_f32_e32 v24, v28, v28
	v_fmac_f32_e32 v25, v30, v30
	v_add_f32_e32 v24, v24, v25
	v_mul_f32_e32 v25, v33, v33
	v_mul_f32_e32 v26, v27, v27
	v_fmac_f32_e32 v25, v32, v32
	v_fmac_f32_e32 v26, v34, v34
	v_add_f32_e32 v25, v25, v26
	v_add_f32_e32 v35, v24, v25
	v_cvt_pk_bf16_f32 v24, v28, v29
	s_waitcnt vmcnt(14)
	v_lshlrev_b32_e32 v28, 16, v136
	v_add_f32_e32 v20, v20, v28
	v_and_b32_e32 v28, 0xffff0000, v136
	v_add_f32_e32 v21, v21, v28
	v_lshlrev_b32_e32 v28, 16, v137
	v_add_f32_e32 v22, v22, v28
	v_and_b32_e32 v28, 0xffff0000, v137
	v_add_f32_e32 v23, v23, v28
	v_lshlrev_b32_e32 v28, 16, v138
	v_add_f32_e32 v28, v16, v28
	v_and_b32_e32 v16, 0xffff0000, v138
	v_add_f32_e32 v29, v17, v16
	v_lshlrev_b32_e32 v16, 16, v139
	v_cvt_pk_bf16_f32 v25, v30, v31
	v_add_f32_e32 v30, v18, v16
	v_and_b32_e32 v16, 0xffff0000, v139
	v_add_f32_e32 v31, v19, v16
	v_mul_f32_e32 v16, v21, v21
	v_mul_f32_e32 v17, v23, v23
	v_fmac_f32_e32 v16, v20, v20
	v_fmac_f32_e32 v17, v22, v22
	v_add_f32_e32 v16, v16, v17
	v_mul_f32_e32 v17, v29, v29
	v_mul_f32_e32 v18, v31, v31
	v_fmac_f32_e32 v17, v28, v28
	v_fmac_f32_e32 v18, v30, v30
	v_add_f32_e32 v17, v17, v18
	v_add_f32_e32 v16, v16, v17
	v_cvt_pk_bf16_f32 v26, v32, v33
	v_add_f32_e32 v32, v35, v16
	ds_bpermute_b32 v33, v112, v32
	v_lshl_add_u64 v[16:17], s[66:67], 0, v[194:195]
	v_cvt_pk_bf16_f32 v27, v34, v27
	global_store_dwordx4 v[16:17], v[24:27], off sc1
	v_cvt_pk_bf16_f32 v18, v20, v21
	s_waitcnt lgkmcnt(0)
	v_add_f32_e32 v16, v32, v33
	ds_bpermute_b32 v17, v113, v16
	v_cvt_pk_bf16_f32 v19, v22, v23
	v_lshl_add_u64 v[22:23], s[64:65], 0, v[194:195]
	v_cvt_pk_bf16_f32 v20, v28, v29
	v_cvt_pk_bf16_f32 v21, v30, v31
	global_store_dwordx4 v[22:23], v[18:21], off sc1
	s_and_saveexec_b64 s[68:69], s[2:3]
	s_cbranch_execz .LBB0_768
	v_lshl_add_u64 v[18:19], v[208:209], 2, s[0:1]
	s_waitcnt lgkmcnt(0)
	v_add_f32_e32 v16, v16, v17
	global_atomic_add_f32 v[18:19], v16, off offset:640
.LBB0_768:
	s_or_b64 exec, exec, s[68:69]
	s_waitcnt vmcnt(15)
	v_lshlrev_b32_e32 v16, 16, v132
	v_add_f32_e32 v12, v12, v16
	v_and_b32_e32 v16, 0xffff0000, v132
	v_add_f32_e32 v13, v13, v16
	v_lshlrev_b32_e32 v16, 16, v133
	v_add_f32_e32 v14, v14, v16
	v_and_b32_e32 v16, 0xffff0000, v133
	v_add_f32_e32 v15, v15, v16
	v_lshlrev_b32_e32 v16, 16, v134
	v_add_f32_e32 v16, v8, v16
	v_and_b32_e32 v8, 0xffff0000, v134
	s_waitcnt lgkmcnt(0)
	v_add_f32_e32 v17, v9, v8
	v_lshlrev_b32_e32 v8, 16, v135
	v_add_f32_e32 v18, v10, v8
	v_and_b32_e32 v8, 0xffff0000, v135
	v_add_f32_e32 v11, v11, v8
	v_mul_f32_e32 v8, v13, v13
	v_mul_f32_e32 v9, v15, v15
	v_fmac_f32_e32 v8, v12, v12
	v_fmac_f32_e32 v9, v14, v14
	v_add_f32_e32 v8, v8, v9
	v_mul_f32_e32 v9, v17, v17
	v_mul_f32_e32 v10, v11, v11
	v_fmac_f32_e32 v9, v16, v16
	v_fmac_f32_e32 v10, v18, v18
	v_add_f32_e32 v9, v9, v10
	v_add_f32_e32 v19, v8, v9
	v_cvt_pk_bf16_f32 v8, v12, v13
	s_waitcnt vmcnt(14)
	v_lshlrev_b32_e32 v12, 16, v128
	v_add_f32_e32 v4, v4, v12
	v_and_b32_e32 v12, 0xffff0000, v128
	v_add_f32_e32 v5, v5, v12
	v_lshlrev_b32_e32 v12, 16, v129
	v_add_f32_e32 v6, v6, v12
	v_and_b32_e32 v12, 0xffff0000, v129
	v_add_f32_e32 v7, v7, v12
	v_lshlrev_b32_e32 v12, 16, v130
	v_add_f32_e32 v12, v0, v12
	v_and_b32_e32 v0, 0xffff0000, v130
	v_add_f32_e32 v13, v1, v0
	v_lshlrev_b32_e32 v0, 16, v131
	v_cvt_pk_bf16_f32 v9, v14, v15
	v_add_f32_e32 v14, v2, v0
	v_and_b32_e32 v0, 0xffff0000, v131
	v_add_f32_e32 v15, v3, v0
	v_mul_f32_e32 v0, v5, v5
	v_mul_f32_e32 v1, v7, v7
	v_fmac_f32_e32 v0, v4, v4
	v_fmac_f32_e32 v1, v6, v6
	v_add_f32_e32 v0, v0, v1
	v_mul_f32_e32 v1, v13, v13
	v_mul_f32_e32 v2, v15, v15
	v_fmac_f32_e32 v1, v12, v12
	v_fmac_f32_e32 v2, v14, v14
	v_add_f32_e32 v1, v1, v2
	v_add_f32_e32 v0, v0, v1
	v_cvt_pk_bf16_f32 v10, v16, v17
	v_add_f32_e32 v16, v19, v0
	ds_bpermute_b32 v17, v112, v16
	v_lshl_add_u64 v[0:1], s[66:67], 0, v[184:185]
	v_cvt_pk_bf16_f32 v11, v18, v11
	global_store_dwordx4 v[0:1], v[8:11], off sc1
	v_cvt_pk_bf16_f32 v2, v4, v5
	s_waitcnt lgkmcnt(0)
	v_add_f32_e32 v0, v16, v17
	ds_bpermute_b32 v1, v113, v0
	v_cvt_pk_bf16_f32 v3, v6, v7
	v_lshl_add_u64 v[6:7], s[64:65], 0, v[184:185]
	v_cvt_pk_bf16_f32 v4, v12, v13
	v_cvt_pk_bf16_f32 v5, v14, v15
	global_store_dwordx4 v[6:7], v[2:5], off sc1
	s_and_saveexec_b64 s[64:65], s[2:3]
	s_cbranch_execz .LBB0_770
	v_lshl_add_u64 v[2:3], v[208:209], 2, s[0:1]
	s_waitcnt lgkmcnt(0)
	v_add_f32_e32 v0, v0, v1
	global_atomic_add_f32 v[2:3], v0, off offset:704
